# cross-lane butterflies without LDS: P4 LayerNorm statistics via v_permlane16/32_swap, mix-build RMSNorm sums via DPP adds (same operand pairs per lane, bit-identical) instead of ds_bpermute round trip
# speedup vs baseline: 1.0127x; 1.0007x over previous
.LBB0_311:
	s_nop 0
	v_lshl_add_u64 v[10:11], s[34:35], 0, v[52:53]
	v_add_co_u32_e32 v60, vcc, 0x27000000, v10
	v_lshl_add_u64 v[74:75], s[34:35], 0, v[54:55]
	s_nop 0
	v_addc_co_u32_e32 v61, vcc, 0, v11, vcc
	v_add_co_u32_e32 v72, vcc, 0x2b000000, v10
	global_load_dwordx4 v[46:49], v[60:61], off nt
	s_nop 0
	v_addc_co_u32_e32 v73, vcc, 0, v11, vcc
	global_load_dwordx4 v[56:59], v[72:73], off nt
	global_load_dwordx4 v[68:71], v[74:75], off offset:-256 nt
	global_load_dwordx4 v[42:45], v[60:61], off offset:1024 nt
	global_load_dwordx4 v[38:41], v[72:73], off offset:1024 nt
	global_load_dwordx4 v[34:37], v[74:75], off offset:-128 nt
	global_load_dwordx4 v[30:33], v[60:61], off offset:2048 nt
	global_load_dwordx4 v[26:29], v[72:73], off offset:2048 nt
	global_load_dwordx4 v[22:25], v[74:75], off nt
	global_load_dwordx4 v[18:21], v[60:61], off offset:3072 nt
	global_load_dwordx4 v[14:17], v[72:73], off offset:3072 nt
	global_load_dwordx4 v[10:13], v[74:75], off offset:128 nt
	s_add_i32 s4, s4, s6
	v_lshl_add_u64 v[52:53], v[52:53], 0, s[10:11]
	v_lshl_add_u64 v[54:55], v[54:55], 0, s[12:13]
	s_cmp_lt_i32 s4, 0x10000
	s_waitcnt vmcnt(9)
	v_lshlrev_b32_e32 v67, 16, v70
	v_and_b32_e32 v70, 0xffff0000, v70
	v_lshlrev_b32_e32 v60, 16, v49
	v_and_b32_e32 v61, 0xffff0000, v49
	v_lshlrev_b32_e32 v72, 16, v59
	v_and_b32_e32 v73, 0xffff0000, v59
	v_pk_add_f32 v[60:61], v[60:61], v[72:73]
	v_lshlrev_b32_e32 v72, 16, v48
	v_and_b32_e32 v73, 0xffff0000, v48
	v_lshlrev_b32_e32 v48, 16, v58
	v_and_b32_e32 v49, 0xffff0000, v58
	v_pk_add_f32 v[48:49], v[72:73], v[48:49]
	v_mov_b32_e32 v58, v60
	v_mov_b32_e32 v59, v48
	v_pk_mul_f32 v[58:59], v[58:59], v[58:59]
	v_mov_b32_e32 v72, v61
	v_mov_b32_e32 v73, v49
	v_pk_fma_f32 v[58:59], v[72:73], v[72:73], v[58:59]
	v_mul_f32_e32 v72, 0xbfb8aa3b, v67
	v_mul_f32_e32 v73, 0xbfb8aa3b, v70
	v_exp_f32_e32 v72, v72
	v_exp_f32_e32 v73, v73
	s_nop 0
	v_pk_add_f32 v[72:73], v[72:73], 1.0 op_sel_hi:[1,0]
	s_nop 0
	s_nop 0
	v_rcp_f32_e32 v74, v73
	s_nop 0
	v_mul_f32_e32 v73, v70, v74
	s_nop 0
	v_lshlrev_b32_e32 v74, 16, v47
	v_and_b32_e32 v75, 0xffff0000, v47
	v_lshlrev_b32_e32 v47, 16, v69
	v_rcp_f32_e32 v70, v72
	s_nop 0
	v_mul_f32_e32 v72, v67, v70
	v_lshlrev_b32_e32 v76, 16, v57
	v_and_b32_e32 v77, 0xffff0000, v57
	v_and_b32_e32 v57, 0xffff0000, v69
	v_mul_f32_e32 v67, 0xbfb8aa3b, v47
	v_pk_add_f32 v[74:75], v[74:75], v[76:77]
	v_exp_f32_e32 v76, v67
	v_mul_f32_e32 v67, 0xbfb8aa3b, v57
	v_exp_f32_e32 v77, v67
	s_nop 0
	v_pk_add_f32 v[76:77], v[76:77], 1.0 op_sel_hi:[1,0]
	s_nop 0
	s_nop 0
	v_rcp_f32_e32 v67, v77
	s_nop 0
	v_mul_f32_e32 v77, v57, v67
	v_and_b32_e32 v79, 0xffff0000, v46
	v_rcp_f32_e32 v57, v76
	s_nop 0
	v_mul_f32_e32 v76, v47, v57
	v_lshlrev_b32_e32 v78, 16, v46
	v_lshlrev_b32_e32 v46, 16, v56
	v_and_b32_e32 v47, 0xffff0000, v56
	v_pk_add_f32 v[46:47], v[78:79], v[46:47]
	v_mov_b32_e32 v57, v74
	v_mov_b32_e32 v56, v46
	v_pk_mul_f32 v[56:57], v[56:57], v[56:57]
	v_mov_b32_e32 v78, v47
	v_mov_b32_e32 v79, v75
	v_lshlrev_b32_e32 v67, 16, v68
	v_and_b32_e32 v70, 0xffff0000, v68
	v_pk_fma_f32 v[56:57], v[78:79], v[78:79], v[56:57]
	v_mul_f32_e32 v68, 0xbfb8aa3b, v67
	v_mul_f32_e32 v69, 0xbfb8aa3b, v70
	v_exp_f32_e32 v68, v68
	v_exp_f32_e32 v69, v69
	v_add_f32_e32 v56, v56, v57
	v_add_f32_e32 v56, v59, v56
	v_add_f32_e32 v56, v58, v56
	v_pk_add_f32 v[68:69], v[68:69], 1.0 op_sel_hi:[1,0]
	s_waitcnt lgkmcnt(0)
	s_nop 1
	v_add_f32_dpp v56, v56, v56 quad_perm:[1,0,3,2] row_mask:0xf bank_mask:0xf
	s_waitcnt lgkmcnt(0)
	s_nop 1
	v_add_f32_dpp v56, v56, v56 quad_perm:[2,3,0,1] row_mask:0xf bank_mask:0xf
	v_rcp_f32_e32 v78, v69
	s_nop 0
	v_mul_f32_e32 v69, v70, v78
	s_waitcnt lgkmcnt(0)
	s_nop 1
	v_add_f32_dpp v56, v56, v56 row_half_mirror row_mask:0xf bank_mask:0xf
	s_waitcnt lgkmcnt(0)
	s_nop 1
	v_add_f32_dpp v56, v56, v56 row_mirror row_mask:0xf bank_mask:0xf
	v_fmamk_f32 v56, v56, 0x3c000000, v65
	v_cmp_gt_f32_e32 vcc, s5, v56
	v_mul_f32_e32 v57, 0x4f800000, v56
	v_rcp_f32_e32 v70, v68
	s_nop 0
	v_mul_f32_e32 v68, v67, v70
	v_cndmask_b32_e32 v56, v56, v57, vcc
	v_sqrt_f32_e32 v57, v56
	s_nop 0
	v_add_u32_e32 v58, -1, v57
	v_fma_f32 v59, -v58, v57, v56
	v_cmp_ge_f32_e64 s[0:1], 0, v59
	v_add_u32_e32 v59, 1, v57
	s_nop 0
	v_cndmask_b32_e64 v58, v57, v58, s[0:1]
	v_fma_f32 v57, -v59, v57, v56
	v_cmp_lt_f32_e64 s[0:1], 0, v57
	s_nop 1
	v_cndmask_b32_e64 v57, v58, v59, s[0:1]
	v_mul_f32_e32 v58, 0x37800000, v57
	v_cndmask_b32_e32 v57, v57, v58, vcc
	v_cmp_class_f32_e32 vcc, v56, v66
	s_nop 1
	v_cndmask_b32_e32 v56, v57, v56, vcc
	s_nop 0
	v_rcp_f32_e32 v56, v56
	s_nop 0
	v_pk_mul_f32 v[48:49], v[48:49], v[56:57] op_sel_hi:[1,0]
	v_pk_mul_f32 v[46:47], v[46:47], v[56:57] op_sel_hi:[1,0]
	v_pk_mul_f32 v[58:59], v[74:75], v[56:57] op_sel_hi:[1,0]
	v_pk_mul_f32 v[48:49], v[6:7], v[48:49]
	v_pk_mul_f32 v[46:47], v[2:3], v[46:47]
	v_pk_mul_f32 v[58:59], v[4:5], v[58:59]
	v_pk_mul_f32 v[48:49], v[72:73], v[48:49]
	v_pk_mul_f32 v[46:47], v[68:69], v[46:47]
	v_pk_mul_f32 v[58:59], v[76:77], v[58:59]
	v_cvt_pk_bf16_f32 v48, v48, v49
	v_lshlrev_b32_e32 v49, 16, v71
	v_and_b32_e32 v67, 0xffff0000, v71
	v_cvt_pk_bf16_f32 v46, v46, v47
	v_cvt_pk_bf16_f32 v47, v58, v59
	v_mul_f32_e32 v57, 0xbfb8aa3b, v49
	v_mul_f32_e32 v59, 0xbfb8aa3b, v67
	v_exp_f32_e32 v58, v57
	v_exp_f32_e32 v59, v59
	v_pk_mul_f32 v[56:57], v[60:61], v[56:57] op_sel_hi:[1,0]
	v_pk_add_f32 v[58:59], v[58:59], 1.0 op_sel_hi:[1,0]
	s_nop 0
	v_pk_mul_f32 v[56:57], v[8:9], v[56:57]
	v_rcp_f32_e32 v60, v59
	s_nop 0
	v_mul_f32_e32 v59, v67, v60
	s_nop 0
	v_rcp_f32_e32 v60, v58
	s_nop 0
	v_mul_f32_e32 v58, v49, v60
	v_pk_mul_f32 v[56:57], v[58:59], v[56:57]
	s_waitcnt vmcnt(6)
	v_lshlrev_b32_e32 v60, 16, v36
	v_cvt_pk_bf16_f32 v49, v56, v57
	v_lshl_add_u64 v[56:57], s[34:35], 0, v[50:51]
	v_add_co_u32_e32 v58, vcc, s7, v56
	v_and_b32_e32 v36, 0xffff0000, v36
	s_nop 0
	v_addc_co_u32_e32 v59, vcc, 0, v57, vcc
	v_add_co_u32_e32 v56, vcc, s14, v56
	v_lshl_add_u64 v[50:51], v[50:51], 0, s[8:9]
	s_nop 0
	v_addc_co_u32_e32 v57, vcc, 0, v57, vcc
	global_store_dwordx4 v[56:57], v[46:49], off offset:-4096
	s_nop 1
	v_lshlrev_b32_e32 v46, 16, v45
	v_and_b32_e32 v47, 0xffff0000, v45
	v_lshlrev_b32_e32 v48, 16, v41
	v_and_b32_e32 v49, 0xffff0000, v41
	v_pk_add_f32 v[46:47], v[46:47], v[48:49]
	v_lshlrev_b32_e32 v48, 16, v44
	v_and_b32_e32 v49, 0xffff0000, v44
	v_lshlrev_b32_e32 v44, 16, v40
	v_and_b32_e32 v45, 0xffff0000, v40
	v_pk_add_f32 v[40:41], v[48:49], v[44:45]
	v_mov_b32_e32 v44, v46
	v_mov_b32_e32 v45, v40
	v_pk_mul_f32 v[44:45], v[44:45], v[44:45]
	v_mov_b32_e32 v48, v47
	v_mov_b32_e32 v49, v41
	v_pk_fma_f32 v[44:45], v[48:49], v[48:49], v[44:45]
	v_mul_f32_e32 v48, 0xbfb8aa3b, v60
	v_mul_f32_e32 v49, 0xbfb8aa3b, v36
	v_exp_f32_e32 v48, v48
	v_exp_f32_e32 v49, v49
	s_nop 0
	v_pk_add_f32 v[48:49], v[48:49], 1.0 op_sel_hi:[1,0]
	s_nop 0
	s_nop 0
	v_rcp_f32_e32 v61, v49
	s_nop 0
	v_mul_f32_e32 v49, v36, v61
	s_nop 0
	v_rcp_f32_e32 v36, v48
	s_nop 0
	v_mul_f32_e32 v48, v60, v36
	v_lshlrev_b32_e32 v36, 16, v35
	v_lshlrev_b32_e32 v60, 16, v43
	v_and_b32_e32 v61, 0xffff0000, v43
	v_lshlrev_b32_e32 v68, 16, v39
	v_and_b32_e32 v69, 0xffff0000, v39
	v_and_b32_e32 v35, 0xffff0000, v35
	v_mul_f32_e32 v39, 0xbfb8aa3b, v36
	v_pk_add_f32 v[60:61], v[60:61], v[68:69]
	v_exp_f32_e32 v68, v39
	v_mul_f32_e32 v39, 0xbfb8aa3b, v35
	v_exp_f32_e32 v69, v39
	s_nop 0
	v_pk_add_f32 v[68:69], v[68:69], 1.0 op_sel_hi:[1,0]
	s_nop 0
	s_nop 0
	v_rcp_f32_e32 v39, v69
	s_nop 0
	v_mul_f32_e32 v69, v35, v39
	v_and_b32_e32 v71, 0xffff0000, v42
	v_rcp_f32_e32 v35, v68
	s_nop 0
	v_mul_f32_e32 v68, v36, v35
	v_lshlrev_b32_e32 v36, 16, v34
	v_and_b32_e32 v67, 0xffff0000, v34
	v_mul_f32_e32 v34, 0xbfb8aa3b, v36
	v_mul_f32_e32 v35, 0xbfb8aa3b, v67
	v_exp_f32_e32 v34, v34
	v_exp_f32_e32 v35, v35
	v_lshlrev_b32_e32 v70, 16, v42
	v_lshlrev_b32_e32 v42, 16, v38
	v_and_b32_e32 v43, 0xffff0000, v38
	v_pk_add_f32 v[42:43], v[70:71], v[42:43]
	v_mov_b32_e32 v39, v60
	v_mov_b32_e32 v38, v42
	v_pk_mul_f32 v[38:39], v[38:39], v[38:39]
	v_mov_b32_e32 v70, v43
	v_mov_b32_e32 v71, v61
	v_pk_add_f32 v[34:35], v[34:35], 1.0 op_sel_hi:[1,0]
	v_pk_fma_f32 v[38:39], v[70:71], v[70:71], v[38:39]
	s_nop 0
	v_rcp_f32_e32 v70, v35
	s_nop 0
	v_mul_f32_e32 v35, v67, v70
	s_nop 0
	v_rcp_f32_e32 v67, v34
	s_nop 0
	v_mul_f32_e32 v34, v36, v67
	v_add_f32_e32 v36, v38, v39
	v_add_f32_e32 v36, v45, v36
	v_add_f32_e32 v36, v44, v36
	s_waitcnt lgkmcnt(0)
	s_nop 1
	v_add_f32_dpp v36, v36, v36 quad_perm:[1,0,3,2] row_mask:0xf bank_mask:0xf
	s_waitcnt lgkmcnt(0)
	s_nop 1
	v_add_f32_dpp v36, v36, v36 quad_perm:[2,3,0,1] row_mask:0xf bank_mask:0xf
	s_waitcnt lgkmcnt(0)
	s_nop 1
	v_add_f32_dpp v36, v36, v36 row_half_mirror row_mask:0xf bank_mask:0xf
	s_waitcnt lgkmcnt(0)
	s_nop 1
	v_add_f32_dpp v36, v36, v36 row_mirror row_mask:0xf bank_mask:0xf
	v_fmamk_f32 v36, v36, 0x3c000000, v65
	v_cmp_gt_f32_e32 vcc, s5, v36
	v_mul_f32_e32 v38, 0x4f800000, v36
	s_nop 0
	v_cndmask_b32_e32 v36, v36, v38, vcc
	v_sqrt_f32_e32 v38, v36
	s_nop 0
	v_add_u32_e32 v39, -1, v38
	v_fma_f32 v44, -v39, v38, v36
	v_cmp_ge_f32_e64 s[0:1], 0, v44
	v_add_u32_e32 v44, 1, v38
	s_nop 0
	v_cndmask_b32_e64 v39, v38, v39, s[0:1]
	v_fma_f32 v38, -v44, v38, v36
	v_cmp_lt_f32_e64 s[0:1], 0, v38
	s_nop 1
	v_cndmask_b32_e64 v38, v39, v44, s[0:1]
	v_mul_f32_e32 v39, 0x37800000, v38
	v_cndmask_b32_e32 v38, v38, v39, vcc
	v_cmp_class_f32_e32 vcc, v36, v66
	s_nop 1
	v_cndmask_b32_e32 v36, v38, v36, vcc
	s_nop 0
	v_rcp_f32_e32 v38, v36
	s_nop 0
	v_pk_mul_f32 v[42:43], v[42:43], v[38:39] op_sel_hi:[1,0]
	v_pk_mul_f32 v[40:41], v[40:41], v[38:39] op_sel_hi:[1,0]
	v_pk_mul_f32 v[42:43], v[2:3], v[42:43]
	v_pk_mul_f32 v[40:41], v[6:7], v[40:41]
	v_pk_mul_f32 v[34:35], v[34:35], v[42:43]
	v_pk_mul_f32 v[42:43], v[60:61], v[38:39] op_sel_hi:[1,0]
	v_cvt_pk_bf16_f32 v34, v34, v35
	v_pk_mul_f32 v[42:43], v[4:5], v[42:43]
	v_pk_mul_f32 v[40:41], v[48:49], v[40:41]
	v_pk_mul_f32 v[42:43], v[68:69], v[42:43]
	v_cvt_pk_bf16_f32 v36, v40, v41
	v_cvt_pk_bf16_f32 v35, v42, v43
	v_lshlrev_b32_e32 v42, 16, v37
	v_and_b32_e32 v37, 0xffff0000, v37
	v_mul_f32_e32 v39, 0xbfb8aa3b, v42
	v_mul_f32_e32 v41, 0xbfb8aa3b, v37
	v_exp_f32_e32 v40, v39
	v_exp_f32_e32 v41, v41
	v_pk_mul_f32 v[38:39], v[46:47], v[38:39] op_sel_hi:[1,0]
	v_pk_add_f32 v[40:41], v[40:41], 1.0 op_sel_hi:[1,0]
	s_nop 0
	v_pk_mul_f32 v[38:39], v[8:9], v[38:39]
	v_rcp_f32_e32 v43, v41
	s_nop 0
	v_mul_f32_e32 v41, v37, v43
	s_nop 0
	v_rcp_f32_e32 v37, v40
	s_nop 0
	v_mul_f32_e32 v40, v42, v37
	v_pk_mul_f32 v[38:39], v[40:41], v[38:39]
	s_nop 0
	v_cvt_pk_bf16_f32 v37, v38, v39
	global_store_dwordx4 v[58:59], v[34:37], off offset:2048
	s_waitcnt vmcnt(5)
	v_lshlrev_b32_e32 v38, 16, v24
	v_and_b32_e32 v24, 0xffff0000, v24
	v_lshlrev_b32_e32 v34, 16, v33
	v_and_b32_e32 v35, 0xffff0000, v33
	v_lshlrev_b32_e32 v36, 16, v29
	v_and_b32_e32 v37, 0xffff0000, v29
	v_pk_add_f32 v[34:35], v[34:35], v[36:37]
	v_lshlrev_b32_e32 v36, 16, v32
	v_and_b32_e32 v37, 0xffff0000, v32
	v_lshlrev_b32_e32 v32, 16, v28
	v_and_b32_e32 v33, 0xffff0000, v28
	v_pk_add_f32 v[28:29], v[36:37], v[32:33]
	v_mov_b32_e32 v32, v34
	v_mov_b32_e32 v33, v28
	v_pk_mul_f32 v[32:33], v[32:33], v[32:33]
	v_mov_b32_e32 v36, v35
	v_mov_b32_e32 v37, v29
	v_pk_fma_f32 v[32:33], v[36:37], v[36:37], v[32:33]
	v_mul_f32_e32 v36, 0xbfb8aa3b, v38
	v_mul_f32_e32 v37, 0xbfb8aa3b, v24
	v_exp_f32_e32 v36, v36
	v_exp_f32_e32 v37, v37
	s_nop 0
	v_pk_add_f32 v[36:37], v[36:37], 1.0 op_sel_hi:[1,0]
	s_nop 0
	s_nop 0
	v_rcp_f32_e32 v39, v37
	s_nop 0
	v_mul_f32_e32 v37, v24, v39
	s_nop 0
	v_rcp_f32_e32 v24, v36
	s_nop 0
	v_mul_f32_e32 v36, v38, v24
	v_lshlrev_b32_e32 v24, 16, v23
	v_lshlrev_b32_e32 v38, 16, v31
	v_and_b32_e32 v39, 0xffff0000, v31
	v_lshlrev_b32_e32 v40, 16, v27
	v_and_b32_e32 v41, 0xffff0000, v27
	v_and_b32_e32 v23, 0xffff0000, v23
	v_mul_f32_e32 v27, 0xbfb8aa3b, v24
	v_pk_add_f32 v[38:39], v[38:39], v[40:41]
	v_exp_f32_e32 v40, v27
	v_mul_f32_e32 v27, 0xbfb8aa3b, v23
	v_exp_f32_e32 v41, v27
	s_nop 0
	v_pk_add_f32 v[40:41], v[40:41], 1.0 op_sel_hi:[1,0]
	s_nop 0
	s_nop 0
	v_rcp_f32_e32 v27, v41
	s_nop 0
	v_mul_f32_e32 v41, v23, v27
	s_nop 0
	v_lshlrev_b32_e32 v42, 16, v30
	v_and_b32_e32 v43, 0xffff0000, v30
	v_lshlrev_b32_e32 v30, 16, v26
	v_and_b32_e32 v31, 0xffff0000, v26
	v_pk_add_f32 v[30:31], v[42:43], v[30:31]
	v_mov_b32_e32 v27, v38
	v_mov_b32_e32 v26, v30
	v_pk_mul_f32 v[26:27], v[26:27], v[26:27]
	v_mov_b32_e32 v42, v31
	v_mov_b32_e32 v43, v39
	v_rcp_f32_e32 v23, v40
	s_nop 0
	v_mul_f32_e32 v40, v24, v23
	v_pk_fma_f32 v[26:27], v[42:43], v[42:43], v[26:27]
	v_lshlrev_b32_e32 v24, 16, v22
	v_and_b32_e32 v42, 0xffff0000, v22
	v_mul_f32_e32 v22, 0xbfb8aa3b, v24
	v_mul_f32_e32 v23, 0xbfb8aa3b, v42
	v_exp_f32_e32 v22, v22
	v_exp_f32_e32 v23, v23
	s_nop 0
	v_pk_add_f32 v[22:23], v[22:23], 1.0 op_sel_hi:[1,0]
	s_nop 0
	s_nop 0
	v_rcp_f32_e32 v43, v23
	s_nop 0
	v_mul_f32_e32 v23, v42, v43
	s_nop 0
	v_rcp_f32_e32 v42, v22
	s_nop 0
	v_mul_f32_e32 v22, v24, v42
	v_add_f32_e32 v24, v26, v27
	v_add_f32_e32 v24, v33, v24
	v_add_f32_e32 v24, v32, v24
	s_waitcnt lgkmcnt(0)
	s_nop 1
	v_add_f32_dpp v24, v24, v24 quad_perm:[1,0,3,2] row_mask:0xf bank_mask:0xf
	s_waitcnt lgkmcnt(0)
	s_nop 1
	v_add_f32_dpp v24, v24, v24 quad_perm:[2,3,0,1] row_mask:0xf bank_mask:0xf
	s_waitcnt lgkmcnt(0)
	s_nop 1
	v_add_f32_dpp v24, v24, v24 row_half_mirror row_mask:0xf bank_mask:0xf
	s_waitcnt lgkmcnt(0)
	s_nop 1
	v_add_f32_dpp v24, v24, v24 row_mirror row_mask:0xf bank_mask:0xf
	v_fmamk_f32 v24, v24, 0x3c000000, v65
	v_cmp_gt_f32_e32 vcc, s5, v24
	v_mul_f32_e32 v26, 0x4f800000, v24
	s_nop 0
	v_cndmask_b32_e32 v24, v24, v26, vcc
	v_sqrt_f32_e32 v26, v24
	s_nop 0
	v_add_u32_e32 v27, -1, v26
	v_fma_f32 v32, -v27, v26, v24
	v_cmp_ge_f32_e64 s[0:1], 0, v32
	v_add_u32_e32 v32, 1, v26
	s_nop 0
	v_cndmask_b32_e64 v27, v26, v27, s[0:1]
	v_fma_f32 v26, -v32, v26, v24
	v_cmp_lt_f32_e64 s[0:1], 0, v26
	s_nop 1
	v_cndmask_b32_e64 v26, v27, v32, s[0:1]
	v_mul_f32_e32 v27, 0x37800000, v26
	v_cndmask_b32_e32 v26, v26, v27, vcc
	v_cmp_class_f32_e32 vcc, v24, v66
	s_nop 1
	v_cndmask_b32_e32 v24, v26, v24, vcc
	s_nop 0
	v_rcp_f32_e32 v26, v24
	s_nop 0
	v_pk_mul_f32 v[30:31], v[30:31], v[26:27] op_sel_hi:[1,0]
	v_pk_mul_f32 v[28:29], v[28:29], v[26:27] op_sel_hi:[1,0]
	v_pk_mul_f32 v[30:31], v[2:3], v[30:31]
	v_pk_mul_f32 v[28:29], v[6:7], v[28:29]
	v_pk_mul_f32 v[22:23], v[22:23], v[30:31]
	v_pk_mul_f32 v[30:31], v[38:39], v[26:27] op_sel_hi:[1,0]
	v_cvt_pk_bf16_f32 v22, v22, v23
	v_pk_mul_f32 v[30:31], v[4:5], v[30:31]
	v_pk_mul_f32 v[28:29], v[36:37], v[28:29]
	v_pk_mul_f32 v[30:31], v[40:41], v[30:31]
	v_cvt_pk_bf16_f32 v24, v28, v29
	v_cvt_pk_bf16_f32 v23, v30, v31
	v_lshlrev_b32_e32 v30, 16, v25
	v_and_b32_e32 v25, 0xffff0000, v25
	v_mul_f32_e32 v27, 0xbfb8aa3b, v30
	v_mul_f32_e32 v29, 0xbfb8aa3b, v25
	v_exp_f32_e32 v28, v27
	v_exp_f32_e32 v29, v29
	v_pk_mul_f32 v[26:27], v[34:35], v[26:27] op_sel_hi:[1,0]
	v_pk_add_f32 v[28:29], v[28:29], 1.0 op_sel_hi:[1,0]
	s_nop 0
	v_pk_mul_f32 v[26:27], v[8:9], v[26:27]
	v_rcp_f32_e32 v31, v29
	s_nop 0
	v_mul_f32_e32 v29, v25, v31
	s_nop 0
	v_rcp_f32_e32 v25, v28
	s_nop 0
	v_mul_f32_e32 v28, v30, v25
	v_pk_mul_f32 v[26:27], v[28:29], v[26:27]
	s_nop 0
	v_cvt_pk_bf16_f32 v25, v26, v27
	global_store_dwordx4 v[56:57], v[22:25], off
	s_waitcnt vmcnt(3)
	v_lshlrev_b32_e32 v26, 16, v12
	v_and_b32_e32 v12, 0xffff0000, v12
	v_lshlrev_b32_e32 v22, 16, v21
	v_and_b32_e32 v23, 0xffff0000, v21
	v_lshlrev_b32_e32 v24, 16, v17
	v_and_b32_e32 v25, 0xffff0000, v17
	v_pk_add_f32 v[22:23], v[22:23], v[24:25]
	v_lshlrev_b32_e32 v24, 16, v20
	v_and_b32_e32 v25, 0xffff0000, v20
	v_lshlrev_b32_e32 v20, 16, v16
	v_and_b32_e32 v21, 0xffff0000, v16
	v_pk_add_f32 v[16:17], v[24:25], v[20:21]
	v_mov_b32_e32 v20, v22
	v_mov_b32_e32 v21, v16
	v_pk_mul_f32 v[20:21], v[20:21], v[20:21]
	v_mov_b32_e32 v24, v23
	v_mov_b32_e32 v25, v17
	v_pk_fma_f32 v[20:21], v[24:25], v[24:25], v[20:21]
	v_mul_f32_e32 v24, 0xbfb8aa3b, v26
	v_mul_f32_e32 v25, 0xbfb8aa3b, v12
	v_exp_f32_e32 v24, v24
	v_exp_f32_e32 v25, v25
	s_nop 0
	v_pk_add_f32 v[24:25], v[24:25], 1.0 op_sel_hi:[1,0]
	s_nop 0
	s_nop 0
	v_rcp_f32_e32 v27, v25
	s_nop 0
	v_mul_f32_e32 v25, v12, v27
	s_nop 0
	v_rcp_f32_e32 v12, v24
	s_nop 0
	v_mul_f32_e32 v24, v26, v12
	v_lshlrev_b32_e32 v12, 16, v11
	v_lshlrev_b32_e32 v26, 16, v19
	v_and_b32_e32 v27, 0xffff0000, v19
	v_lshlrev_b32_e32 v28, 16, v15
	v_and_b32_e32 v29, 0xffff0000, v15
	v_and_b32_e32 v11, 0xffff0000, v11
	v_mul_f32_e32 v15, 0xbfb8aa3b, v12
	v_pk_add_f32 v[26:27], v[26:27], v[28:29]
	v_exp_f32_e32 v28, v15
	v_mul_f32_e32 v15, 0xbfb8aa3b, v11
	v_exp_f32_e32 v29, v15
	s_nop 0
	v_pk_add_f32 v[28:29], v[28:29], 1.0 op_sel_hi:[1,0]
	s_nop 0
	s_nop 0
	v_rcp_f32_e32 v15, v29
	s_nop 0
	v_mul_f32_e32 v29, v11, v15
	s_nop 0
	v_lshlrev_b32_e32 v30, 16, v18
	v_and_b32_e32 v31, 0xffff0000, v18
	v_lshlrev_b32_e32 v18, 16, v14
	v_and_b32_e32 v19, 0xffff0000, v14
	v_pk_add_f32 v[18:19], v[30:31], v[18:19]
	v_mov_b32_e32 v15, v26
	v_mov_b32_e32 v14, v18
	v_pk_mul_f32 v[14:15], v[14:15], v[14:15]
	v_mov_b32_e32 v30, v19
	v_mov_b32_e32 v31, v27
	v_rcp_f32_e32 v11, v28
	s_nop 0
	v_mul_f32_e32 v28, v12, v11
	v_pk_fma_f32 v[14:15], v[30:31], v[30:31], v[14:15]
	v_lshlrev_b32_e32 v12, 16, v10
	v_and_b32_e32 v30, 0xffff0000, v10
	v_mul_f32_e32 v10, 0xbfb8aa3b, v12
	v_mul_f32_e32 v11, 0xbfb8aa3b, v30
	v_exp_f32_e32 v10, v10
	v_exp_f32_e32 v11, v11
	s_nop 0
	v_pk_add_f32 v[10:11], v[10:11], 1.0 op_sel_hi:[1,0]
	s_nop 0
	s_nop 0
	v_rcp_f32_e32 v31, v11
	s_nop 0
	v_mul_f32_e32 v11, v30, v31
	s_nop 0
	v_rcp_f32_e32 v30, v10
	s_nop 0
	v_mul_f32_e32 v10, v12, v30
	v_add_f32_e32 v12, v14, v15
	v_add_f32_e32 v12, v21, v12
	v_add_f32_e32 v12, v20, v12
	s_waitcnt lgkmcnt(0)
	s_nop 1
	v_add_f32_dpp v12, v12, v12 quad_perm:[1,0,3,2] row_mask:0xf bank_mask:0xf
	s_waitcnt lgkmcnt(0)
	s_nop 1
	v_add_f32_dpp v12, v12, v12 quad_perm:[2,3,0,1] row_mask:0xf bank_mask:0xf
	s_waitcnt lgkmcnt(0)
	s_nop 1
	v_add_f32_dpp v12, v12, v12 row_half_mirror row_mask:0xf bank_mask:0xf
	s_waitcnt lgkmcnt(0)
	s_nop 1
	v_add_f32_dpp v12, v12, v12 row_mirror row_mask:0xf bank_mask:0xf
	v_fmamk_f32 v12, v12, 0x3c000000, v65
	v_cmp_gt_f32_e32 vcc, s5, v12
	v_mul_f32_e32 v14, 0x4f800000, v12
	s_nop 0
	v_cndmask_b32_e32 v12, v12, v14, vcc
	v_sqrt_f32_e32 v14, v12
	s_nop 0
	v_add_u32_e32 v15, -1, v14
	v_fma_f32 v20, -v15, v14, v12
	v_cmp_ge_f32_e64 s[0:1], 0, v20
	v_add_u32_e32 v20, 1, v14
	s_nop 0
	v_cndmask_b32_e64 v15, v14, v15, s[0:1]
	v_fma_f32 v14, -v20, v14, v12
	v_cmp_lt_f32_e64 s[0:1], 0, v14
	s_nop 1
	v_cndmask_b32_e64 v14, v15, v20, s[0:1]
	v_mul_f32_e32 v15, 0x37800000, v14
	v_cndmask_b32_e32 v14, v14, v15, vcc
	v_cmp_class_f32_e32 vcc, v12, v66
	s_nop 1
	v_cndmask_b32_e32 v12, v14, v12, vcc
	s_nop 0
	v_rcp_f32_e32 v14, v12
	s_nop 0
	v_pk_mul_f32 v[18:19], v[18:19], v[14:15] op_sel_hi:[1,0]
	v_pk_mul_f32 v[16:17], v[16:17], v[14:15] op_sel_hi:[1,0]
	v_pk_mul_f32 v[18:19], v[2:3], v[18:19]
	v_pk_mul_f32 v[16:17], v[6:7], v[16:17]
	v_pk_mul_f32 v[10:11], v[10:11], v[18:19]
	v_pk_mul_f32 v[18:19], v[26:27], v[14:15] op_sel_hi:[1,0]
	v_cvt_pk_bf16_f32 v10, v10, v11
	v_pk_mul_f32 v[18:19], v[4:5], v[18:19]
	v_pk_mul_f32 v[16:17], v[24:25], v[16:17]
	v_pk_mul_f32 v[18:19], v[28:29], v[18:19]
	v_cvt_pk_bf16_f32 v12, v16, v17
	v_cvt_pk_bf16_f32 v11, v18, v19
	v_lshlrev_b32_e32 v18, 16, v13
	v_and_b32_e32 v13, 0xffff0000, v13
	v_mul_f32_e32 v15, 0xbfb8aa3b, v18
	v_mul_f32_e32 v17, 0xbfb8aa3b, v13
	v_exp_f32_e32 v16, v15
	v_exp_f32_e32 v17, v17
	v_pk_mul_f32 v[14:15], v[22:23], v[14:15] op_sel_hi:[1,0]
	v_pk_add_f32 v[16:17], v[16:17], 1.0 op_sel_hi:[1,0]
	s_nop 0
	v_pk_mul_f32 v[14:15], v[8:9], v[14:15]
	v_rcp_f32_e32 v19, v17
	s_nop 0
	v_mul_f32_e32 v17, v13, v19
	s_nop 0
	v_rcp_f32_e32 v13, v16
	s_nop 0
	v_mul_f32_e32 v16, v18, v13
	v_pk_mul_f32 v[14:15], v[16:17], v[14:15]
	s_nop 0
	v_cvt_pk_bf16_f32 v13, v14, v15
	global_store_dwordx4 v[56:57], v[10:13], off offset:2048
	s_cbranch_scc1 .LBB0_311

.LBB0_391:
	s_lshl_b32 s39, s14, 8
	v_add_u32_e32 v176, s39, v180
	v_lshl_or_b32 v128, s46, 8, v182
	v_ashrrev_i32_e32 v177, 31, v176
	v_ashrrev_i32_e32 v129, 31, v128
	v_lshlrev_b64 v[130:131], 11, v[176:177]
	v_lshl_add_u64 v[132:133], s[16:17], 0, v[130:131]
	v_lshlrev_b64 v[130:131], 1, v[128:129]
	v_lshl_add_u64 v[132:133], v[132:133], 0, v[130:131]
	s_mov_b64 s[80:81], 0x8000
	s_mov_b64 s[82:83], 0x28000
	v_lshrrev_b32_e32 v252, 4, v203
	v_lshlrev_b32_e32 v252, 3, v252
	v_mov_b32_e32 v253, 0
	v_lshl_add_u64 v[254:255], v[132:133], 0, v[252:253]
	global_load_dwordx4 v[210:213], v[254:255], off nt
	global_load_dwordx4 v[214:217], v[254:255], off offset:256 nt
	v_lshl_add_u64 v[254:255], v[254:255], 0, s[80:81]
	global_load_dwordx4 v[218:221], v[254:255], off nt
	global_load_dwordx4 v[222:225], v[254:255], off offset:256 nt
	v_lshl_add_u64 v[254:255], v[254:255], 0, s[80:81]
	global_load_dwordx4 v[226:229], v[254:255], off nt
	global_load_dwordx4 v[230:233], v[254:255], off offset:256 nt
	v_lshl_add_u64 v[254:255], v[254:255], 0, s[80:81]
	global_load_dwordx4 v[234:237], v[254:255], off nt
	global_load_dwordx4 v[238:241], v[254:255], off offset:256 nt
	v_lshl_add_u64 v[254:255], v[254:255], 0, s[82:83]
	global_load_dwordx4 v[242:245], v[254:255], off nt
	global_load_dwordx4 v[246:249], v[254:255], off offset:256 nt
	v_lshl_add_u64 v[254:255], v[254:255], 0, s[80:81]
	v_or_b32_e32 v140, 16, v176
	v_ashrrev_i32_e32 v141, 31, v140
	v_lshlrev_b64 v[140:141], 11, v[140:141]
	v_lshl_add_u64 v[140:141], s[16:17], 0, v[140:141]
	v_lshl_add_u64 v[140:141], v[140:141], 0, v[130:131]
	s_waitcnt vmcnt(8)
	v_permlane16_swap_b32_e32 v210, v212
	v_permlane16_swap_b32_e32 v211, v213
	v_permlane16_swap_b32_e32 v214, v216
	v_permlane16_swap_b32_e32 v215, v217
	v_permlane32_swap_b32_e32 v210, v212
	v_permlane32_swap_b32_e32 v211, v213
	v_permlane32_swap_b32_e32 v214, v216
	v_permlane32_swap_b32_e32 v215, v217
	v_mov_b32_e32 v134, v210
	v_mov_b32_e32 v135, v211
	v_mov_b32_e32 v136, v212
	v_mov_b32_e32 v137, v213
	v_mov_b32_e32 v138, v214
	v_mov_b32_e32 v139, v215
	v_mov_b32_e32 v132, v216
	v_mov_b32_e32 v133, v217
	global_load_dwordx4 v[210:213], v[254:255], off nt
	global_load_dwordx4 v[214:217], v[254:255], off offset:256 nt
	v_lshl_add_u64 v[254:255], v[254:255], 0, s[80:81]
	v_lshlrev_b32_e32 v142, 16, v134
	v_and_b32_e32 v143, 0xffff0000, v134
	v_lshlrev_b32_e32 v134, 16, v135
	v_and_b32_e32 v135, 0xffff0000, v135
	v_lshlrev_b32_e32 v144, 16, v136
	v_and_b32_e32 v145, 0xffff0000, v136
	v_lshlrev_b32_e32 v136, 16, v137
	v_and_b32_e32 v137, 0xffff0000, v137
	v_lshlrev_b32_e32 v146, 16, v138
	v_and_b32_e32 v147, 0xffff0000, v138
	v_lshlrev_b32_e32 v138, 16, v139
	v_and_b32_e32 v139, 0xffff0000, v139
	v_lshlrev_b32_e32 v148, 16, v132
	v_and_b32_e32 v149, 0xffff0000, v132
	v_lshlrev_b32_e32 v132, 16, v133
	v_and_b32_e32 v133, 0xffff0000, v133
	v_pk_fma_f32 v[46:47], v[134:135], s[36:37], v[46:47] op_sel_hi:[1,0,1]
	v_pk_fma_f32 v[44:45], v[142:143], s[36:37], v[44:45] op_sel_hi:[1,0,1]
	v_pk_fma_f32 v[42:43], v[136:137], s[36:37], v[42:43] op_sel_hi:[1,0,1]
	v_pk_fma_f32 v[40:41], v[144:145], s[36:37], v[40:41] op_sel_hi:[1,0,1]
	v_pk_fma_f32 v[38:39], v[138:139], s[36:37], v[38:39] op_sel_hi:[1,0,1]
	v_pk_fma_f32 v[36:37], v[146:147], s[36:37], v[36:37] op_sel_hi:[1,0,1]
	v_pk_fma_f32 v[34:35], v[132:133], s[36:37], v[34:35] op_sel_hi:[1,0,1]
	v_pk_fma_f32 v[32:33], v[148:149], s[36:37], v[32:33] op_sel_hi:[1,0,1]
	s_nop 0
	s_waitcnt vmcnt(8)
	v_permlane16_swap_b32_e32 v218, v220
	v_permlane16_swap_b32_e32 v219, v221
	v_permlane16_swap_b32_e32 v222, v224
	v_permlane16_swap_b32_e32 v223, v225
	v_permlane32_swap_b32_e32 v218, v220
	v_permlane32_swap_b32_e32 v219, v221
	v_permlane32_swap_b32_e32 v222, v224
	v_permlane32_swap_b32_e32 v223, v225
	v_mov_b32_e32 v132, v218
	v_mov_b32_e32 v133, v219
	v_mov_b32_e32 v134, v220
	v_mov_b32_e32 v135, v221
	v_mov_b32_e32 v136, v222
	v_mov_b32_e32 v137, v223
	v_mov_b32_e32 v138, v224
	v_mov_b32_e32 v139, v225
	global_load_dwordx4 v[218:221], v[254:255], off nt
	global_load_dwordx4 v[222:225], v[254:255], off offset:256 nt
	v_lshl_add_u64 v[254:255], v[254:255], 0, s[80:81]
	v_or_b32_e32 v140, 32, v176
	v_ashrrev_i32_e32 v141, 31, v140
	v_lshlrev_b64 v[140:141], 11, v[140:141]
	v_lshl_add_u64 v[140:141], s[16:17], 0, v[140:141]
	v_lshl_add_u64 v[140:141], v[140:141], 0, v[130:131]
	v_lshlrev_b32_e32 v142, 16, v132
	v_and_b32_e32 v143, 0xffff0000, v132
	v_lshlrev_b32_e32 v132, 16, v133
	v_and_b32_e32 v133, 0xffff0000, v133
	v_lshlrev_b32_e32 v144, 16, v134
	v_and_b32_e32 v145, 0xffff0000, v134
	v_lshlrev_b32_e32 v134, 16, v135
	v_and_b32_e32 v135, 0xffff0000, v135
	v_lshlrev_b32_e32 v146, 16, v136
	v_and_b32_e32 v147, 0xffff0000, v136
	v_lshlrev_b32_e32 v136, 16, v137
	v_and_b32_e32 v137, 0xffff0000, v137
	v_lshlrev_b32_e32 v148, 16, v138
	v_and_b32_e32 v149, 0xffff0000, v138
	v_lshlrev_b32_e32 v138, 16, v139
	v_and_b32_e32 v139, 0xffff0000, v139
	v_pk_fma_f32 v[90:91], v[132:133], s[36:37], v[90:91] op_sel_hi:[1,0,1]
	v_pk_fma_f32 v[88:89], v[142:143], s[36:37], v[88:89] op_sel_hi:[1,0,1]
	v_pk_fma_f32 v[58:59], v[134:135], s[36:37], v[58:59] op_sel_hi:[1,0,1]
	v_pk_fma_f32 v[56:57], v[144:145], s[36:37], v[56:57] op_sel_hi:[1,0,1]
	v_pk_fma_f32 v[54:55], v[136:137], s[36:37], v[54:55] op_sel_hi:[1,0,1]
	v_pk_fma_f32 v[52:53], v[146:147], s[36:37], v[52:53] op_sel_hi:[1,0,1]
	v_pk_fma_f32 v[50:51], v[138:139], s[36:37], v[50:51] op_sel_hi:[1,0,1]
	v_pk_fma_f32 v[48:49], v[148:149], s[36:37], v[48:49] op_sel_hi:[1,0,1]
	s_nop 0
	s_waitcnt vmcnt(8)
	v_permlane16_swap_b32_e32 v226, v228
	v_permlane16_swap_b32_e32 v227, v229
	v_permlane16_swap_b32_e32 v230, v232
	v_permlane16_swap_b32_e32 v231, v233
	v_permlane32_swap_b32_e32 v226, v228
	v_permlane32_swap_b32_e32 v227, v229
	v_permlane32_swap_b32_e32 v230, v232
	v_permlane32_swap_b32_e32 v231, v233
	v_mov_b32_e32 v132, v226
	v_mov_b32_e32 v133, v227
	v_mov_b32_e32 v134, v228
	v_mov_b32_e32 v135, v229
	v_mov_b32_e32 v136, v230
	v_mov_b32_e32 v137, v231
	v_mov_b32_e32 v138, v232
	v_mov_b32_e32 v139, v233
	global_load_dwordx4 v[226:229], v[254:255], off nt
	global_load_dwordx4 v[230:233], v[254:255], off offset:256 nt
	v_or_b32_e32 v140, 48, v176
	v_ashrrev_i32_e32 v141, 31, v140
	v_lshlrev_b64 v[140:141], 11, v[140:141]
	v_lshl_add_u64 v[140:141], s[16:17], 0, v[140:141]
	v_lshl_add_u64 v[140:141], v[140:141], 0, v[130:131]
	v_lshlrev_b32_e32 v142, 16, v132
	v_and_b32_e32 v143, 0xffff0000, v132
	v_lshlrev_b32_e32 v132, 16, v133
	v_and_b32_e32 v133, 0xffff0000, v133
	v_lshlrev_b32_e32 v144, 16, v134
	v_and_b32_e32 v145, 0xffff0000, v134
	v_lshlrev_b32_e32 v134, 16, v135
	v_and_b32_e32 v135, 0xffff0000, v135
	v_lshlrev_b32_e32 v146, 16, v136
	v_and_b32_e32 v147, 0xffff0000, v136
	v_lshlrev_b32_e32 v136, 16, v137
	v_and_b32_e32 v137, 0xffff0000, v137
	v_lshlrev_b32_e32 v148, 16, v138
	v_and_b32_e32 v149, 0xffff0000, v138
	v_lshlrev_b32_e32 v138, 16, v139
	v_and_b32_e32 v139, 0xffff0000, v139
	v_pk_fma_f32 v[98:99], v[132:133], s[36:37], v[98:99] op_sel_hi:[1,0,1]
	v_pk_fma_f32 v[96:97], v[142:143], s[36:37], v[96:97] op_sel_hi:[1,0,1]
	v_pk_fma_f32 v[82:83], v[134:135], s[36:37], v[82:83] op_sel_hi:[1,0,1]
	v_pk_fma_f32 v[80:81], v[144:145], s[36:37], v[80:81] op_sel_hi:[1,0,1]
	v_pk_fma_f32 v[78:79], v[136:137], s[36:37], v[78:79] op_sel_hi:[1,0,1]
	v_pk_fma_f32 v[76:77], v[146:147], s[36:37], v[76:77] op_sel_hi:[1,0,1]
	v_pk_fma_f32 v[70:71], v[138:139], s[36:37], v[70:71] op_sel_hi:[1,0,1]
	v_pk_fma_f32 v[68:69], v[148:149], s[36:37], v[68:69] op_sel_hi:[1,0,1]
	s_nop 0
	s_waitcnt vmcnt(8)
	v_permlane16_swap_b32_e32 v234, v236
	v_permlane16_swap_b32_e32 v235, v237
	v_permlane16_swap_b32_e32 v238, v240
	v_permlane16_swap_b32_e32 v239, v241
	v_permlane32_swap_b32_e32 v234, v236
	v_permlane32_swap_b32_e32 v235, v237
	v_permlane32_swap_b32_e32 v238, v240
	v_permlane32_swap_b32_e32 v239, v241
	v_mov_b32_e32 v132, v234
	v_mov_b32_e32 v133, v235
	v_mov_b32_e32 v134, v236
	v_mov_b32_e32 v135, v237
	v_mov_b32_e32 v136, v238
	v_mov_b32_e32 v137, v239
	v_mov_b32_e32 v138, v240
	v_mov_b32_e32 v139, v241
	v_add_u32_e32 v140, 0x80, v176
	v_ashrrev_i32_e32 v141, 31, v140
	v_lshlrev_b64 v[140:141], 11, v[140:141]
	v_lshl_add_u64 v[140:141], s[16:17], 0, v[140:141]
	v_lshl_add_u64 v[140:141], v[140:141], 0, v[130:131]
	v_lshlrev_b32_e32 v142, 16, v132
	v_and_b32_e32 v143, 0xffff0000, v132
	v_lshlrev_b32_e32 v132, 16, v133
	v_and_b32_e32 v133, 0xffff0000, v133
	v_lshlrev_b32_e32 v144, 16, v134
	v_and_b32_e32 v145, 0xffff0000, v134
	v_lshlrev_b32_e32 v134, 16, v135
	v_and_b32_e32 v135, 0xffff0000, v135
	v_lshlrev_b32_e32 v146, 16, v136
	v_and_b32_e32 v147, 0xffff0000, v136
	v_lshlrev_b32_e32 v136, 16, v137
	v_and_b32_e32 v137, 0xffff0000, v137
	v_lshlrev_b32_e32 v148, 16, v138
	v_and_b32_e32 v149, 0xffff0000, v138
	v_lshlrev_b32_e32 v138, 16, v139
	v_and_b32_e32 v139, 0xffff0000, v139
	v_pk_fma_f32 v[122:123], v[132:133], s[36:37], v[122:123] op_sel_hi:[1,0,1]
	v_pk_fma_f32 v[120:121], v[142:143], s[36:37], v[120:121] op_sel_hi:[1,0,1]
	v_pk_fma_f32 v[114:115], v[134:135], s[36:37], v[114:115] op_sel_hi:[1,0,1]
	v_pk_fma_f32 v[112:113], v[144:145], s[36:37], v[112:113] op_sel_hi:[1,0,1]
	v_pk_fma_f32 v[106:107], v[136:137], s[36:37], v[106:107] op_sel_hi:[1,0,1]
	v_pk_fma_f32 v[104:105], v[146:147], s[36:37], v[104:105] op_sel_hi:[1,0,1]
	v_pk_fma_f32 v[86:87], v[138:139], s[36:37], v[86:87] op_sel_hi:[1,0,1]
	v_pk_fma_f32 v[84:85], v[148:149], s[36:37], v[84:85] op_sel_hi:[1,0,1]
	s_nop 0
	s_waitcnt vmcnt(6)
	v_permlane16_swap_b32_e32 v242, v244
	v_permlane16_swap_b32_e32 v243, v245
	v_permlane16_swap_b32_e32 v246, v248
	v_permlane16_swap_b32_e32 v247, v249
	v_permlane32_swap_b32_e32 v242, v244
	v_permlane32_swap_b32_e32 v243, v245
	v_permlane32_swap_b32_e32 v246, v248
	v_permlane32_swap_b32_e32 v247, v249
	v_mov_b32_e32 v132, v242
	v_mov_b32_e32 v133, v243
	v_mov_b32_e32 v134, v244
	v_mov_b32_e32 v135, v245
	v_mov_b32_e32 v136, v246
	v_mov_b32_e32 v137, v247
	v_mov_b32_e32 v138, v248
	v_mov_b32_e32 v139, v249
	v_add_u32_e32 v140, 0x90, v176
	v_ashrrev_i32_e32 v141, 31, v140
	v_lshlrev_b64 v[140:141], 11, v[140:141]
	v_lshl_add_u64 v[140:141], s[16:17], 0, v[140:141]
	v_lshl_add_u64 v[140:141], v[140:141], 0, v[130:131]
	v_lshlrev_b32_e32 v142, 16, v132
	v_and_b32_e32 v143, 0xffff0000, v132
	v_lshlrev_b32_e32 v132, 16, v133
	v_and_b32_e32 v133, 0xffff0000, v133
	v_lshlrev_b32_e32 v144, 16, v134
	v_and_b32_e32 v145, 0xffff0000, v134
	v_lshlrev_b32_e32 v134, 16, v135
	v_and_b32_e32 v135, 0xffff0000, v135
	v_lshlrev_b32_e32 v146, 16, v136
	v_and_b32_e32 v147, 0xffff0000, v136
	v_lshlrev_b32_e32 v136, 16, v137
	v_and_b32_e32 v137, 0xffff0000, v137
	v_lshlrev_b32_e32 v148, 16, v138
	v_and_b32_e32 v149, 0xffff0000, v138
	v_lshlrev_b32_e32 v138, 16, v139
	v_and_b32_e32 v139, 0xffff0000, v139
	v_pk_fma_f32 v[14:15], v[132:133], s[36:37], v[14:15] op_sel_hi:[1,0,1]
	v_pk_fma_f32 v[12:13], v[142:143], s[36:37], v[12:13] op_sel_hi:[1,0,1]
	v_pk_fma_f32 v[10:11], v[134:135], s[36:37], v[10:11] op_sel_hi:[1,0,1]
	v_pk_fma_f32 v[8:9], v[144:145], s[36:37], v[8:9] op_sel_hi:[1,0,1]
	v_pk_fma_f32 v[6:7], v[136:137], s[36:37], v[6:7] op_sel_hi:[1,0,1]
	v_pk_fma_f32 v[4:5], v[146:147], s[36:37], v[4:5] op_sel_hi:[1,0,1]
	v_pk_fma_f32 v[2:3], v[138:139], s[36:37], v[2:3] op_sel_hi:[1,0,1]
	v_pk_fma_f32 v[0:1], v[148:149], s[36:37], v[0:1] op_sel_hi:[1,0,1]
	s_nop 0
	s_waitcnt vmcnt(4)
	v_permlane16_swap_b32_e32 v210, v212
	v_permlane16_swap_b32_e32 v211, v213
	v_permlane16_swap_b32_e32 v214, v216
	v_permlane16_swap_b32_e32 v215, v217
	v_permlane32_swap_b32_e32 v210, v212
	v_permlane32_swap_b32_e32 v211, v213
	v_permlane32_swap_b32_e32 v214, v216
	v_permlane32_swap_b32_e32 v215, v217
	v_mov_b32_e32 v132, v210
	v_mov_b32_e32 v133, v211
	v_mov_b32_e32 v134, v212
	v_mov_b32_e32 v135, v213
	v_mov_b32_e32 v136, v214
	v_mov_b32_e32 v137, v215
	v_mov_b32_e32 v138, v216
	v_mov_b32_e32 v139, v217
	v_add_u32_e32 v140, 0xa0, v176
	v_ashrrev_i32_e32 v141, 31, v140
	v_lshlrev_b64 v[140:141], 11, v[140:141]
	v_lshl_add_u64 v[140:141], s[16:17], 0, v[140:141]
	v_lshl_add_u64 v[140:141], v[140:141], 0, v[130:131]
	v_lshlrev_b32_e32 v142, 16, v132
	v_and_b32_e32 v143, 0xffff0000, v132
	v_lshlrev_b32_e32 v132, 16, v133
	v_and_b32_e32 v133, 0xffff0000, v133
	v_lshlrev_b32_e32 v144, 16, v134
	v_and_b32_e32 v145, 0xffff0000, v134
	v_lshlrev_b32_e32 v134, 16, v135
	v_and_b32_e32 v135, 0xffff0000, v135
	v_lshlrev_b32_e32 v146, 16, v136
	v_and_b32_e32 v147, 0xffff0000, v136
	v_lshlrev_b32_e32 v136, 16, v137
	v_and_b32_e32 v137, 0xffff0000, v137
	v_lshlrev_b32_e32 v148, 16, v138
	v_and_b32_e32 v149, 0xffff0000, v138
	v_lshlrev_b32_e32 v138, 16, v139
	v_and_b32_e32 v139, 0xffff0000, v139
	v_pk_fma_f32 v[30:31], v[132:133], s[36:37], v[30:31] op_sel_hi:[1,0,1]
	v_pk_fma_f32 v[28:29], v[142:143], s[36:37], v[28:29] op_sel_hi:[1,0,1]
	v_pk_fma_f32 v[26:27], v[134:135], s[36:37], v[26:27] op_sel_hi:[1,0,1]
	v_pk_fma_f32 v[24:25], v[144:145], s[36:37], v[24:25] op_sel_hi:[1,0,1]
	v_pk_fma_f32 v[22:23], v[136:137], s[36:37], v[22:23] op_sel_hi:[1,0,1]
	v_pk_fma_f32 v[20:21], v[146:147], s[36:37], v[20:21] op_sel_hi:[1,0,1]
	v_pk_fma_f32 v[18:19], v[138:139], s[36:37], v[18:19] op_sel_hi:[1,0,1]
	v_pk_fma_f32 v[16:17], v[148:149], s[36:37], v[16:17] op_sel_hi:[1,0,1]
	v_add_u32_e32 v142, 0xb0, v176
	s_waitcnt vmcnt(2)
	v_permlane16_swap_b32_e32 v218, v220
	v_permlane16_swap_b32_e32 v219, v221
	v_permlane16_swap_b32_e32 v222, v224
	v_permlane16_swap_b32_e32 v223, v225
	v_permlane32_swap_b32_e32 v218, v220
	v_permlane32_swap_b32_e32 v219, v221
	v_permlane32_swap_b32_e32 v222, v224
	v_permlane32_swap_b32_e32 v223, v225
	v_mov_b32_e32 v134, v218
	v_mov_b32_e32 v135, v219
	v_mov_b32_e32 v136, v220
	v_mov_b32_e32 v137, v221
	v_mov_b32_e32 v138, v222
	v_mov_b32_e32 v139, v223
	v_mov_b32_e32 v140, v224
	v_mov_b32_e32 v141, v225
	v_ashrrev_i32_e32 v143, 31, v142
	v_lshlrev_b64 v[142:143], 11, v[142:143]
	v_lshl_add_u64 v[142:143], s[16:17], 0, v[142:143]
	v_lshl_add_u64 v[130:131], v[142:143], 0, v[130:131]
	v_mov_b32_e32 v142, v45
	v_mov_b32_e32 v143, v46
	v_mov_b32_e32 v144, v44
	v_mov_b32_e32 v145, v47
	v_pk_add_f32 v[142:143], v[142:143], v[144:145]
	v_mov_b32_e32 v146, v41
	v_mov_b32_e32 v147, v42
	v_and_b32_e32 v133, 64, v203
	v_xor_b32_e32 v132, 16, v203
	v_add_u32_e32 v133, 64, v133
	v_cmp_lt_i32_e32 vcc, v132, v133
	v_lshlrev_b32_e32 v148, 16, v134
	v_and_b32_e32 v149, 0xffff0000, v134
	v_lshlrev_b32_e32 v134, 16, v135
	v_and_b32_e32 v135, 0xffff0000, v135
	v_lshlrev_b32_e32 v150, 16, v136
	v_and_b32_e32 v151, 0xffff0000, v136
	v_lshlrev_b32_e32 v136, 16, v137
	v_and_b32_e32 v137, 0xffff0000, v137
	v_lshlrev_b32_e32 v152, 16, v138
	v_and_b32_e32 v153, 0xffff0000, v138
	v_lshlrev_b32_e32 v138, 16, v139
	v_and_b32_e32 v139, 0xffff0000, v139
	v_lshlrev_b32_e32 v154, 16, v140
	v_and_b32_e32 v155, 0xffff0000, v140
	v_lshlrev_b32_e32 v140, 16, v141
	v_and_b32_e32 v141, 0xffff0000, v141
	v_pk_fma_f32 v[94:95], v[134:135], s[36:37], v[94:95] op_sel_hi:[1,0,1]
	v_pk_fma_f32 v[92:93], v[148:149], s[36:37], v[92:93] op_sel_hi:[1,0,1]
	v_pk_fma_f32 v[74:75], v[136:137], s[36:37], v[74:75] op_sel_hi:[1,0,1]
	v_pk_fma_f32 v[72:73], v[150:151], s[36:37], v[72:73] op_sel_hi:[1,0,1]
	v_pk_fma_f32 v[66:67], v[138:139], s[36:37], v[66:67] op_sel_hi:[1,0,1]
	v_pk_fma_f32 v[64:65], v[152:153], s[36:37], v[64:65] op_sel_hi:[1,0,1]
	v_pk_fma_f32 v[62:63], v[140:141], s[36:37], v[62:63] op_sel_hi:[1,0,1]
	v_pk_fma_f32 v[60:61], v[154:155], s[36:37], v[60:61] op_sel_hi:[1,0,1]
	v_mov_b32_e32 v134, v40
	v_mov_b32_e32 v135, v43
	v_add_f32_e32 v141, v36, v37
	v_add_f32_e32 v149, v38, v39
	v_mov_b32_e32 v140, v32
	v_mov_b32_e32 v148, v33
	v_pk_add_f32 v[130:131], v[146:147], v[134:135]
	v_pk_add_f32 v[134:135], v[140:141], v[148:149]
	v_add_f32_e32 v140, v142, v143
	v_pk_add_f32 v[130:131], v[130:131], v[130:131] op_sel_hi:[0,1]
	v_mov_b32_e32 v152, v35
	v_add_f32_e32 v153, 0, v140
	v_mov_b32_e32 v130, v34
	v_pk_add_f32 v[130:131], v[130:131], v[152:153]
	v_cndmask_b32_e32 v132, v203, v132, vcc
	v_pk_add_f32 v[130:131], v[134:135], v[130:131]
	v_lshlrev_b32_e32 v132, 2, v132
	v_add_f32_e32 v131, v130, v131
	v_mov_b32_e32 v134, v131
	s_nop 1
	v_permlane16_swap_b32_e32 v134, v131
	s_nop 1
	v_xor_b32_e32 v130, 32, v203
	v_cmp_lt_i32_e32 vcc, v130, v133
	s_waitcnt lgkmcnt(0)
	v_add_f32_e32 v131, v131, v134
	v_cndmask_b32_e32 v130, v203, v130, vcc
	v_lshlrev_b32_e32 v130, 2, v130
	v_mov_b32_e32 v133, v131
	s_nop 1
	v_permlane32_swap_b32_e32 v133, v131
	s_nop 1
	s_waitcnt lgkmcnt(0)
	v_add_f32_e32 v131, v131, v133
	v_fmamk_f32 v134, v131, 0xbc800000, v47
	v_fmamk_f32 v140, v131, 0xbc800000, v45
	v_fmamk_f32 v142, v131, 0xbc800000, v43
	v_fmamk_f32 v146, v131, 0xbc800000, v41
	v_fmamk_f32 v133, v131, 0xbc800000, v46
	v_fmamk_f32 v135, v131, 0xbc800000, v44
	v_fmamk_f32 v141, v131, 0xbc800000, v42
	v_fmamk_f32 v143, v131, 0xbc800000, v40
	v_fmamk_f32 v148, v131, 0xbc800000, v39
	v_fmamk_f32 v152, v131, 0xbc800000, v37
	v_mul_f32_e32 v140, v140, v140
	v_mul_f32_e32 v134, v134, v134
	v_mul_f32_e32 v146, v146, v146
	v_mul_f32_e32 v142, v142, v142
	v_fmamk_f32 v147, v131, 0xbc800000, v38
	v_fmamk_f32 v149, v131, 0xbc800000, v36
	v_fmamk_f32 v154, v131, 0xbc800000, v35
	v_fmamk_f32 v156, v131, 0xbc800000, v33
	v_mul_f32_e32 v152, v152, v152
	v_mul_f32_e32 v148, v148, v148
	v_fmac_f32_e32 v140, v135, v135
	v_fmac_f32_e32 v134, v133, v133
	v_fmac_f32_e32 v146, v143, v143
	v_fmac_f32_e32 v142, v141, v141
	v_fmamk_f32 v153, v131, 0xbc800000, v34
	v_fmamk_f32 v155, v131, 0xbc800000, v32
	v_mul_f32_e32 v156, v156, v156
	v_mul_f32_e32 v154, v154, v154
	v_fmac_f32_e32 v152, v149, v149
	v_fmac_f32_e32 v148, v147, v147
	v_add_f32_e32 v133, v140, v134
	v_add_f32_e32 v134, v146, v142
	v_fmac_f32_e32 v156, v155, v155
	v_fmac_f32_e32 v154, v153, v153
	v_add_f32_e32 v135, v152, v148
	v_add_f32_e32 v133, v133, v134
	v_add_f32_e32 v140, v156, v154
	v_add_f32_e32 v133, v135, v133
	v_add_f32_e32 v133, v140, v133
	v_mov_b32_e32 v134, v133
	s_nop 1
	v_permlane16_swap_b32_e32 v134, v133
	s_nop 1
	s_waitcnt lgkmcnt(0)
	v_add_f32_e32 v133, v133, v134
	v_mov_b32_e32 v134, v133
	s_nop 1
	v_permlane32_swap_b32_e32 v134, v133
	s_nop 1
	s_waitcnt vmcnt(0)
	v_permlane16_swap_b32_e32 v226, v228
	v_permlane16_swap_b32_e32 v227, v229
	v_permlane16_swap_b32_e32 v230, v232
	v_permlane16_swap_b32_e32 v231, v233
	v_permlane32_swap_b32_e32 v226, v228
	v_permlane32_swap_b32_e32 v227, v229
	v_permlane32_swap_b32_e32 v230, v232
	v_permlane32_swap_b32_e32 v231, v233
	v_mov_b32_e32 v136, v226
	v_mov_b32_e32 v137, v227
	v_mov_b32_e32 v138, v228
	v_mov_b32_e32 v139, v229
	v_mov_b32_e32 v150, v230
	v_mov_b32_e32 v151, v231
	v_mov_b32_e32 v144, v232
	v_mov_b32_e32 v145, v233
	v_lshlrev_b32_e32 v140, 16, v136
	v_and_b32_e32 v141, 0xffff0000, v136
	v_lshlrev_b32_e32 v136, 16, v137
	v_and_b32_e32 v137, 0xffff0000, v137
	v_lshlrev_b32_e32 v142, 16, v138
	v_and_b32_e32 v143, 0xffff0000, v138
	v_lshlrev_b32_e32 v138, 16, v139
	v_and_b32_e32 v139, 0xffff0000, v139
	v_lshlrev_b32_e32 v146, 16, v150
	v_and_b32_e32 v147, 0xffff0000, v150
	v_lshlrev_b32_e32 v148, 16, v151
	v_and_b32_e32 v149, 0xffff0000, v151
	v_lshlrev_b32_e32 v150, 16, v144
	v_and_b32_e32 v151, 0xffff0000, v144
	v_lshlrev_b32_e32 v144, 16, v145
	v_and_b32_e32 v145, 0xffff0000, v145
	v_pk_fma_f32 v[126:127], v[136:137], s[36:37], v[126:127] op_sel_hi:[1,0,1]
	v_pk_fma_f32 v[124:125], v[140:141], s[36:37], v[124:125] op_sel_hi:[1,0,1]
	v_pk_fma_f32 v[118:119], v[138:139], s[36:37], v[118:119] op_sel_hi:[1,0,1]
	v_pk_fma_f32 v[116:117], v[142:143], s[36:37], v[116:117] op_sel_hi:[1,0,1]
	v_pk_fma_f32 v[110:111], v[148:149], s[36:37], v[110:111] op_sel_hi:[1,0,1]
	v_pk_fma_f32 v[108:109], v[146:147], s[36:37], v[108:109] op_sel_hi:[1,0,1]
	v_pk_fma_f32 v[102:103], v[144:145], s[36:37], v[102:103] op_sel_hi:[1,0,1]
	v_pk_fma_f32 v[100:101], v[150:151], s[36:37], v[100:101] op_sel_hi:[1,0,1]
	s_nop 0
	s_and_saveexec_b64 s[48:49], s[12:13]
	s_cbranch_execz .LBB0_393
	v_mul_f32_e32 v136, 0x3c800000, v131
	s_waitcnt lgkmcnt(0)
	v_add_f32_e32 v137, v133, v134
	ds_write_b64 v208, v[136:137]
.LBB0_393:
	s_or_b64 exec, exec, s[48:49]
	s_waitcnt lgkmcnt(0)
	v_mov_b32_e32 v134, v89
	v_mov_b32_e32 v135, v90
	v_mov_b32_e32 v136, v88
	v_mov_b32_e32 v137, v91
	v_pk_add_f32 v[134:135], v[134:135], v[136:137]
	v_mov_b32_e32 v136, v57
	v_mov_b32_e32 v137, v58
	v_mov_b32_e32 v138, v56
	v_mov_b32_e32 v139, v59
	v_pk_add_f32 v[136:137], v[136:137], v[138:139]
	v_add_f32_e32 v131, v134, v135
	v_pk_add_f32 v[136:137], v[136:137], v[136:137] op_sel_hi:[0,1]
	v_add_f32_e32 v135, 0, v131
	v_add_f32_e32 v139, v52, v53
	v_add_f32_e32 v141, v54, v55
	v_mov_b32_e32 v138, v48
	v_mov_b32_e32 v140, v49
	v_mov_b32_e32 v136, v50
	v_mov_b32_e32 v134, v51
	v_pk_add_f32 v[138:139], v[138:139], v[140:141]
	v_pk_add_f32 v[134:135], v[136:137], v[134:135]
	s_nop 0
	v_pk_add_f32 v[134:135], v[138:139], v[134:135]
	s_nop 0
	v_add_f32_e32 v131, v134, v135
	v_mov_b32_e32 v133, v131
	s_nop 1
	v_permlane16_swap_b32_e32 v133, v131
	s_nop 1
	s_waitcnt lgkmcnt(0)
	v_add_f32_e32 v131, v131, v133
	v_mov_b32_e32 v133, v131
	s_nop 1
	v_permlane32_swap_b32_e32 v133, v131
	s_nop 1
	s_waitcnt lgkmcnt(0)
	v_add_f32_e32 v131, v131, v133
	v_fmamk_f32 v134, v131, 0xbc800000, v91
	v_fmamk_f32 v136, v131, 0xbc800000, v89
	v_fmamk_f32 v133, v131, 0xbc800000, v90
	v_fmamk_f32 v135, v131, 0xbc800000, v88
	v_mul_f32_e32 v136, v136, v136
	v_mul_f32_e32 v134, v134, v134
	v_fmac_f32_e32 v136, v135, v135
	v_fmac_f32_e32 v134, v133, v133
	v_fmamk_f32 v135, v131, 0xbc800000, v59
	v_fmamk_f32 v137, v131, 0xbc800000, v57
	v_add_f32_e32 v133, v136, v134
	v_fmamk_f32 v134, v131, 0xbc800000, v58
	v_fmamk_f32 v136, v131, 0xbc800000, v56
	v_mul_f32_e32 v137, v137, v137
	v_mul_f32_e32 v135, v135, v135
	v_fmac_f32_e32 v137, v136, v136
	v_fmac_f32_e32 v135, v134, v134
	v_add_f32_e32 v134, v137, v135
	v_fmamk_f32 v135, v131, 0xbc800000, v55
	v_fmamk_f32 v137, v131, 0xbc800000, v53
	v_add_f32_e32 v133, v133, v134
	v_fmamk_f32 v134, v131, 0xbc800000, v54
	v_fmamk_f32 v136, v131, 0xbc800000, v52
	v_mul_f32_e32 v137, v137, v137
	v_mul_f32_e32 v135, v135, v135
	v_fmac_f32_e32 v137, v136, v136
	v_fmac_f32_e32 v135, v134, v134
	v_add_f32_e32 v134, v137, v135
	v_fmamk_f32 v135, v131, 0xbc800000, v51
	v_fmamk_f32 v137, v131, 0xbc800000, v49
	v_add_f32_e32 v133, v134, v133
	v_fmamk_f32 v134, v131, 0xbc800000, v50
	v_fmamk_f32 v136, v131, 0xbc800000, v48
	v_mul_f32_e32 v137, v137, v137
	v_mul_f32_e32 v135, v135, v135
	v_fmac_f32_e32 v137, v136, v136
	v_fmac_f32_e32 v135, v134, v134
	v_add_f32_e32 v134, v137, v135
	v_add_f32_e32 v133, v134, v133
	v_mov_b32_e32 v134, v133
	s_nop 1
	v_permlane16_swap_b32_e32 v134, v133
	s_nop 1
	s_waitcnt lgkmcnt(0)
	v_add_f32_e32 v133, v133, v134
	v_mov_b32_e32 v134, v133
	s_nop 1
	v_permlane32_swap_b32_e32 v134, v133
	s_nop 1
	s_and_saveexec_b64 s[48:49], s[12:13]
	s_cbranch_execz .LBB0_395
	v_mul_f32_e32 v136, 0x3c800000, v131
	s_waitcnt lgkmcnt(0)
	v_add_f32_e32 v137, v133, v134
	ds_write_b64 v208, v[136:137] offset:512
.LBB0_395:
	s_or_b64 exec, exec, s[48:49]
	s_waitcnt lgkmcnt(0)
	v_mov_b32_e32 v134, v97
	v_mov_b32_e32 v135, v98
	v_mov_b32_e32 v136, v96
	v_mov_b32_e32 v137, v99
	v_pk_add_f32 v[134:135], v[134:135], v[136:137]
	v_mov_b32_e32 v136, v81
	v_mov_b32_e32 v137, v82
	v_mov_b32_e32 v138, v80
	v_mov_b32_e32 v139, v83
	v_pk_add_f32 v[136:137], v[136:137], v[138:139]
	v_add_f32_e32 v131, v134, v135
	v_pk_add_f32 v[136:137], v[136:137], v[136:137] op_sel_hi:[0,1]
	v_add_f32_e32 v135, 0, v131
	v_add_f32_e32 v139, v76, v77
	v_add_f32_e32 v141, v78, v79
	v_mov_b32_e32 v138, v68
	v_mov_b32_e32 v140, v69
	v_mov_b32_e32 v136, v70
	v_mov_b32_e32 v134, v71
	v_pk_add_f32 v[138:139], v[138:139], v[140:141]
	v_pk_add_f32 v[134:135], v[136:137], v[134:135]
	s_nop 0
	v_pk_add_f32 v[134:135], v[138:139], v[134:135]
	s_nop 0
	v_add_f32_e32 v131, v134, v135
	v_mov_b32_e32 v133, v131
	s_nop 1
	v_permlane16_swap_b32_e32 v133, v131
	s_nop 1
	s_waitcnt lgkmcnt(0)
	v_add_f32_e32 v131, v131, v133
	v_mov_b32_e32 v133, v131
	s_nop 1
	v_permlane32_swap_b32_e32 v133, v131
	s_nop 1
	s_waitcnt lgkmcnt(0)
	v_add_f32_e32 v131, v131, v133
	v_fmamk_f32 v134, v131, 0xbc800000, v99
	v_fmamk_f32 v136, v131, 0xbc800000, v97
	v_fmamk_f32 v133, v131, 0xbc800000, v98
	v_fmamk_f32 v135, v131, 0xbc800000, v96
	v_mul_f32_e32 v136, v136, v136
	v_mul_f32_e32 v134, v134, v134
	v_fmac_f32_e32 v136, v135, v135
	v_fmac_f32_e32 v134, v133, v133
	v_fmamk_f32 v135, v131, 0xbc800000, v83
	v_fmamk_f32 v137, v131, 0xbc800000, v81
	v_add_f32_e32 v133, v136, v134
	v_fmamk_f32 v134, v131, 0xbc800000, v82
	v_fmamk_f32 v136, v131, 0xbc800000, v80
	v_mul_f32_e32 v137, v137, v137
	v_mul_f32_e32 v135, v135, v135
	v_fmac_f32_e32 v137, v136, v136
	v_fmac_f32_e32 v135, v134, v134
	v_add_f32_e32 v134, v137, v135
	v_fmamk_f32 v135, v131, 0xbc800000, v79
	v_fmamk_f32 v137, v131, 0xbc800000, v77
	v_add_f32_e32 v133, v133, v134
	v_fmamk_f32 v134, v131, 0xbc800000, v78
	v_fmamk_f32 v136, v131, 0xbc800000, v76
	v_mul_f32_e32 v137, v137, v137
	v_mul_f32_e32 v135, v135, v135
	v_fmac_f32_e32 v137, v136, v136
	v_fmac_f32_e32 v135, v134, v134
	v_add_f32_e32 v134, v137, v135
	v_fmamk_f32 v135, v131, 0xbc800000, v71
	v_fmamk_f32 v137, v131, 0xbc800000, v69
	v_add_f32_e32 v133, v134, v133
	v_fmamk_f32 v134, v131, 0xbc800000, v70
	v_fmamk_f32 v136, v131, 0xbc800000, v68
	v_mul_f32_e32 v137, v137, v137
	v_mul_f32_e32 v135, v135, v135
	v_fmac_f32_e32 v137, v136, v136
	v_fmac_f32_e32 v135, v134, v134
	v_add_f32_e32 v134, v137, v135
	v_add_f32_e32 v133, v134, v133
	v_mov_b32_e32 v134, v133
	s_nop 1
	v_permlane16_swap_b32_e32 v134, v133
	s_nop 1
	s_waitcnt lgkmcnt(0)
	v_add_f32_e32 v133, v133, v134
	v_mov_b32_e32 v134, v133
	s_nop 1
	v_permlane32_swap_b32_e32 v134, v133
	s_nop 1
	s_and_saveexec_b64 s[48:49], s[12:13]
	s_cbranch_execz .LBB0_397
	v_mul_f32_e32 v136, 0x3c800000, v131
	s_waitcnt lgkmcnt(0)
	v_add_f32_e32 v137, v133, v134
	ds_write_b64 v208, v[136:137] offset:1024
.LBB0_397:
	s_or_b64 exec, exec, s[48:49]
	s_waitcnt lgkmcnt(0)
	v_mov_b32_e32 v134, v121
	v_mov_b32_e32 v135, v122
	v_mov_b32_e32 v136, v120
	v_mov_b32_e32 v137, v123
	v_pk_add_f32 v[134:135], v[134:135], v[136:137]
	v_mov_b32_e32 v136, v113
	v_mov_b32_e32 v137, v114
	v_mov_b32_e32 v138, v112
	v_mov_b32_e32 v139, v115
	v_pk_add_f32 v[136:137], v[136:137], v[138:139]
	v_add_f32_e32 v131, v134, v135
	v_pk_add_f32 v[136:137], v[136:137], v[136:137] op_sel_hi:[0,1]
	v_add_f32_e32 v135, 0, v131
	v_add_f32_e32 v139, v104, v105
	v_add_f32_e32 v141, v106, v107
	v_mov_b32_e32 v138, v84
	v_mov_b32_e32 v140, v85
	v_mov_b32_e32 v136, v86
	v_mov_b32_e32 v134, v87
	v_pk_add_f32 v[138:139], v[138:139], v[140:141]
	v_pk_add_f32 v[134:135], v[136:137], v[134:135]
	s_nop 0
	v_pk_add_f32 v[134:135], v[138:139], v[134:135]
	s_nop 0
	v_add_f32_e32 v131, v134, v135
	v_mov_b32_e32 v133, v131
	s_nop 1
	v_permlane16_swap_b32_e32 v133, v131
	s_nop 1
	s_waitcnt lgkmcnt(0)
	v_add_f32_e32 v131, v131, v133
	v_mov_b32_e32 v133, v131
	s_nop 1
	v_permlane32_swap_b32_e32 v133, v131
	s_nop 1
	s_waitcnt lgkmcnt(0)
	v_add_f32_e32 v131, v131, v133
	v_fmamk_f32 v134, v131, 0xbc800000, v123
	v_fmamk_f32 v136, v131, 0xbc800000, v121
	v_fmamk_f32 v133, v131, 0xbc800000, v122
	v_fmamk_f32 v135, v131, 0xbc800000, v120
	v_mul_f32_e32 v136, v136, v136
	v_mul_f32_e32 v134, v134, v134
	v_fmac_f32_e32 v136, v135, v135
	v_fmac_f32_e32 v134, v133, v133
	v_fmamk_f32 v135, v131, 0xbc800000, v115
	v_fmamk_f32 v137, v131, 0xbc800000, v113
	v_add_f32_e32 v133, v136, v134
	v_fmamk_f32 v134, v131, 0xbc800000, v114
	v_fmamk_f32 v136, v131, 0xbc800000, v112
	v_mul_f32_e32 v137, v137, v137
	v_mul_f32_e32 v135, v135, v135
	v_fmac_f32_e32 v137, v136, v136
	v_fmac_f32_e32 v135, v134, v134
	v_add_f32_e32 v134, v137, v135
	v_fmamk_f32 v135, v131, 0xbc800000, v107
	v_fmamk_f32 v137, v131, 0xbc800000, v105
	v_add_f32_e32 v133, v133, v134
	v_fmamk_f32 v134, v131, 0xbc800000, v106
	v_fmamk_f32 v136, v131, 0xbc800000, v104
	v_mul_f32_e32 v137, v137, v137
	v_mul_f32_e32 v135, v135, v135
	v_fmac_f32_e32 v137, v136, v136
	v_fmac_f32_e32 v135, v134, v134
	v_add_f32_e32 v134, v137, v135
	v_fmamk_f32 v135, v131, 0xbc800000, v87
	v_fmamk_f32 v137, v131, 0xbc800000, v85
	v_add_f32_e32 v133, v134, v133
	v_fmamk_f32 v134, v131, 0xbc800000, v86
	v_fmamk_f32 v136, v131, 0xbc800000, v84
	v_mul_f32_e32 v137, v137, v137
	v_mul_f32_e32 v135, v135, v135
	v_fmac_f32_e32 v137, v136, v136
	v_fmac_f32_e32 v135, v134, v134
	v_add_f32_e32 v134, v137, v135
	v_add_f32_e32 v133, v134, v133
	v_mov_b32_e32 v134, v133
	s_nop 1
	v_permlane16_swap_b32_e32 v134, v133
	s_nop 1
	s_waitcnt lgkmcnt(0)
	v_add_f32_e32 v133, v133, v134
	v_mov_b32_e32 v134, v133
	s_nop 1
	v_permlane32_swap_b32_e32 v134, v133
	s_nop 1
	s_and_saveexec_b64 s[48:49], s[12:13]
	s_cbranch_execz .LBB0_399
	v_mul_f32_e32 v136, 0x3c800000, v131
	s_waitcnt lgkmcnt(0)
	v_add_f32_e32 v137, v133, v134
	ds_write_b64 v208, v[136:137] offset:1536
.LBB0_399:
	s_or_b64 exec, exec, s[48:49]
	s_waitcnt lgkmcnt(0)
	v_mov_b32_e32 v134, v13
	v_mov_b32_e32 v135, v14
	v_mov_b32_e32 v136, v12
	v_mov_b32_e32 v137, v15
	v_pk_add_f32 v[134:135], v[134:135], v[136:137]
	v_mov_b32_e32 v136, v9
	v_mov_b32_e32 v137, v10
	v_mov_b32_e32 v138, v8
	v_mov_b32_e32 v139, v11
	v_pk_add_f32 v[136:137], v[136:137], v[138:139]
	v_add_f32_e32 v131, v134, v135
	v_pk_add_f32 v[136:137], v[136:137], v[136:137] op_sel_hi:[0,1]
	v_add_f32_e32 v135, 0, v131
	v_add_f32_e32 v139, v4, v5
	v_add_f32_e32 v141, v6, v7
	v_mov_b32_e32 v138, v0
	v_mov_b32_e32 v140, v1
	v_mov_b32_e32 v136, v2
	v_mov_b32_e32 v134, v3
	v_pk_add_f32 v[138:139], v[138:139], v[140:141]
	v_pk_add_f32 v[134:135], v[136:137], v[134:135]
	s_nop 0
	v_pk_add_f32 v[134:135], v[138:139], v[134:135]
	s_nop 0
	v_add_f32_e32 v131, v134, v135
	v_mov_b32_e32 v133, v131
	s_nop 1
	v_permlane16_swap_b32_e32 v133, v131
	s_nop 1
	s_waitcnt lgkmcnt(0)
	v_add_f32_e32 v131, v131, v133
	v_mov_b32_e32 v133, v131
	s_nop 1
	v_permlane32_swap_b32_e32 v133, v131
	s_nop 1
	s_waitcnt lgkmcnt(0)
	v_add_f32_e32 v131, v131, v133
	v_fmamk_f32 v134, v131, 0xbc800000, v15
	v_fmamk_f32 v136, v131, 0xbc800000, v13
	v_fmamk_f32 v133, v131, 0xbc800000, v14
	v_fmamk_f32 v135, v131, 0xbc800000, v12
	v_mul_f32_e32 v136, v136, v136
	v_mul_f32_e32 v134, v134, v134
	v_fmac_f32_e32 v136, v135, v135
	v_fmac_f32_e32 v134, v133, v133
	v_fmamk_f32 v135, v131, 0xbc800000, v11
	v_fmamk_f32 v137, v131, 0xbc800000, v9
	v_add_f32_e32 v133, v136, v134
	v_fmamk_f32 v134, v131, 0xbc800000, v10
	v_fmamk_f32 v136, v131, 0xbc800000, v8
	v_mul_f32_e32 v137, v137, v137
	v_mul_f32_e32 v135, v135, v135
	v_fmac_f32_e32 v137, v136, v136
	v_fmac_f32_e32 v135, v134, v134
	v_add_f32_e32 v134, v137, v135
	v_fmamk_f32 v135, v131, 0xbc800000, v7
	v_fmamk_f32 v137, v131, 0xbc800000, v5
	v_add_f32_e32 v133, v133, v134
	v_fmamk_f32 v134, v131, 0xbc800000, v6
	v_fmamk_f32 v136, v131, 0xbc800000, v4
	v_mul_f32_e32 v137, v137, v137
	v_mul_f32_e32 v135, v135, v135
	v_fmac_f32_e32 v137, v136, v136
	v_fmac_f32_e32 v135, v134, v134
	v_add_f32_e32 v134, v137, v135
	v_fmamk_f32 v135, v131, 0xbc800000, v3
	v_fmamk_f32 v137, v131, 0xbc800000, v1
	v_add_f32_e32 v133, v134, v133
	v_fmamk_f32 v134, v131, 0xbc800000, v2
	v_fmamk_f32 v136, v131, 0xbc800000, v0
	v_mul_f32_e32 v137, v137, v137
	v_mul_f32_e32 v135, v135, v135
	v_fmac_f32_e32 v137, v136, v136
	v_fmac_f32_e32 v135, v134, v134
	v_add_f32_e32 v134, v137, v135
	v_add_f32_e32 v133, v134, v133
	v_mov_b32_e32 v134, v133
	s_nop 1
	v_permlane16_swap_b32_e32 v134, v133
	s_nop 1
	s_waitcnt lgkmcnt(0)
	v_add_f32_e32 v133, v133, v134
	v_mov_b32_e32 v134, v133
	s_nop 1
	v_permlane32_swap_b32_e32 v134, v133
	s_nop 1
	s_and_saveexec_b64 s[48:49], s[12:13]
	s_cbranch_execz .LBB0_401
	v_mul_f32_e32 v136, 0x3c800000, v131
	s_waitcnt lgkmcnt(0)
	v_add_f32_e32 v137, v133, v134
	ds_write_b64 v208, v[136:137] offset:4096
.LBB0_401:
	s_or_b64 exec, exec, s[48:49]
	s_waitcnt lgkmcnt(0)
	v_mov_b32_e32 v134, v29
	v_mov_b32_e32 v135, v30
	v_mov_b32_e32 v136, v28
	v_mov_b32_e32 v137, v31
	v_pk_add_f32 v[134:135], v[134:135], v[136:137]
	v_mov_b32_e32 v136, v25
	v_mov_b32_e32 v137, v26
	v_mov_b32_e32 v138, v24
	v_mov_b32_e32 v139, v27
	v_pk_add_f32 v[136:137], v[136:137], v[138:139]
	v_add_f32_e32 v131, v134, v135
	v_pk_add_f32 v[136:137], v[136:137], v[136:137] op_sel_hi:[0,1]
	v_add_f32_e32 v135, 0, v131
	v_add_f32_e32 v139, v20, v21
	v_add_f32_e32 v141, v22, v23
	v_mov_b32_e32 v138, v16
	v_mov_b32_e32 v140, v17
	v_mov_b32_e32 v136, v18
	v_mov_b32_e32 v134, v19
	v_pk_add_f32 v[138:139], v[138:139], v[140:141]
	v_pk_add_f32 v[134:135], v[136:137], v[134:135]
	s_nop 0
	v_pk_add_f32 v[134:135], v[138:139], v[134:135]
	s_nop 0
	v_add_f32_e32 v131, v134, v135
	v_mov_b32_e32 v133, v131
	s_nop 1
	v_permlane16_swap_b32_e32 v133, v131
	s_nop 1
	s_waitcnt lgkmcnt(0)
	v_add_f32_e32 v131, v131, v133
	v_mov_b32_e32 v133, v131
	s_nop 1
	v_permlane32_swap_b32_e32 v133, v131
	s_nop 1
	s_waitcnt lgkmcnt(0)
	v_add_f32_e32 v131, v131, v133
	v_fmamk_f32 v134, v131, 0xbc800000, v31
	v_fmamk_f32 v136, v131, 0xbc800000, v29
	v_fmamk_f32 v133, v131, 0xbc800000, v30
	v_fmamk_f32 v135, v131, 0xbc800000, v28
	v_mul_f32_e32 v136, v136, v136
	v_mul_f32_e32 v134, v134, v134
	v_fmac_f32_e32 v136, v135, v135
	v_fmac_f32_e32 v134, v133, v133
	v_fmamk_f32 v135, v131, 0xbc800000, v27
	v_fmamk_f32 v137, v131, 0xbc800000, v25
	v_add_f32_e32 v133, v136, v134
	v_fmamk_f32 v134, v131, 0xbc800000, v26
	v_fmamk_f32 v136, v131, 0xbc800000, v24
	v_mul_f32_e32 v137, v137, v137
	v_mul_f32_e32 v135, v135, v135
	v_fmac_f32_e32 v137, v136, v136
	v_fmac_f32_e32 v135, v134, v134
	v_add_f32_e32 v134, v137, v135
	v_fmamk_f32 v135, v131, 0xbc800000, v23
	v_fmamk_f32 v137, v131, 0xbc800000, v21
	v_add_f32_e32 v133, v133, v134
	v_fmamk_f32 v134, v131, 0xbc800000, v22
	v_fmamk_f32 v136, v131, 0xbc800000, v20
	v_mul_f32_e32 v137, v137, v137
	v_mul_f32_e32 v135, v135, v135
	v_fmac_f32_e32 v137, v136, v136
	v_fmac_f32_e32 v135, v134, v134
	v_add_f32_e32 v134, v137, v135
	v_fmamk_f32 v135, v131, 0xbc800000, v19
	v_fmamk_f32 v137, v131, 0xbc800000, v17
	v_add_f32_e32 v133, v134, v133
	v_fmamk_f32 v134, v131, 0xbc800000, v18
	v_fmamk_f32 v136, v131, 0xbc800000, v16
	v_mul_f32_e32 v137, v137, v137
	v_mul_f32_e32 v135, v135, v135
	v_fmac_f32_e32 v137, v136, v136
	v_fmac_f32_e32 v135, v134, v134
	v_add_f32_e32 v134, v137, v135
	v_add_f32_e32 v133, v134, v133
	v_mov_b32_e32 v134, v133
	s_nop 1
	v_permlane16_swap_b32_e32 v134, v133
	s_nop 1
	s_waitcnt lgkmcnt(0)
	v_add_f32_e32 v133, v133, v134
	v_mov_b32_e32 v134, v133
	s_nop 1
	v_permlane32_swap_b32_e32 v134, v133
	s_nop 1
	s_and_saveexec_b64 s[48:49], s[12:13]
	s_cbranch_execz .LBB0_403
	v_mul_f32_e32 v136, 0x3c800000, v131
	s_waitcnt lgkmcnt(0)
	v_add_f32_e32 v137, v133, v134
	ds_write_b64 v208, v[136:137] offset:4608
.LBB0_403:
	s_or_b64 exec, exec, s[48:49]
	s_waitcnt lgkmcnt(0)
	v_mov_b32_e32 v134, v93
	v_mov_b32_e32 v135, v94
	v_mov_b32_e32 v136, v92
	v_mov_b32_e32 v137, v95
	v_pk_add_f32 v[134:135], v[134:135], v[136:137]
	v_mov_b32_e32 v136, v73
	v_mov_b32_e32 v137, v74
	v_mov_b32_e32 v138, v72
	v_mov_b32_e32 v139, v75
	v_pk_add_f32 v[136:137], v[136:137], v[138:139]
	v_add_f32_e32 v131, v134, v135
	v_pk_add_f32 v[136:137], v[136:137], v[136:137] op_sel_hi:[0,1]
	v_add_f32_e32 v135, 0, v131
	v_add_f32_e32 v139, v64, v65
	v_add_f32_e32 v141, v66, v67
	v_mov_b32_e32 v138, v60
	v_mov_b32_e32 v140, v61
	v_mov_b32_e32 v136, v62
	v_mov_b32_e32 v134, v63
	v_pk_add_f32 v[138:139], v[138:139], v[140:141]
	v_pk_add_f32 v[134:135], v[136:137], v[134:135]
	s_nop 0
	v_pk_add_f32 v[134:135], v[138:139], v[134:135]
	s_nop 0
	v_add_f32_e32 v131, v134, v135
	v_mov_b32_e32 v133, v131
	s_nop 1
	v_permlane16_swap_b32_e32 v133, v131
	s_nop 1
	s_waitcnt lgkmcnt(0)
	v_add_f32_e32 v131, v131, v133
	v_mov_b32_e32 v133, v131
	s_nop 1
	v_permlane32_swap_b32_e32 v133, v131
	s_nop 1
	s_waitcnt lgkmcnt(0)
	v_add_f32_e32 v131, v131, v133
	v_fmamk_f32 v134, v131, 0xbc800000, v95
	v_fmamk_f32 v136, v131, 0xbc800000, v93
	v_fmamk_f32 v133, v131, 0xbc800000, v94
	v_fmamk_f32 v135, v131, 0xbc800000, v92
	v_mul_f32_e32 v136, v136, v136
	v_mul_f32_e32 v134, v134, v134
	v_fmac_f32_e32 v136, v135, v135
	v_fmac_f32_e32 v134, v133, v133
	v_fmamk_f32 v135, v131, 0xbc800000, v75
	v_fmamk_f32 v137, v131, 0xbc800000, v73
	v_add_f32_e32 v133, v136, v134
	v_fmamk_f32 v134, v131, 0xbc800000, v74
	v_fmamk_f32 v136, v131, 0xbc800000, v72
	v_mul_f32_e32 v137, v137, v137
	v_mul_f32_e32 v135, v135, v135
	v_fmac_f32_e32 v137, v136, v136
	v_fmac_f32_e32 v135, v134, v134
	v_add_f32_e32 v134, v137, v135
	v_fmamk_f32 v135, v131, 0xbc800000, v67
	v_fmamk_f32 v137, v131, 0xbc800000, v65
	v_add_f32_e32 v133, v133, v134
	v_fmamk_f32 v134, v131, 0xbc800000, v66
	v_fmamk_f32 v136, v131, 0xbc800000, v64
	v_mul_f32_e32 v137, v137, v137
	v_mul_f32_e32 v135, v135, v135
	v_fmac_f32_e32 v137, v136, v136
	v_fmac_f32_e32 v135, v134, v134
	v_add_f32_e32 v134, v137, v135
	v_fmamk_f32 v135, v131, 0xbc800000, v63
	v_fmamk_f32 v137, v131, 0xbc800000, v61
	v_add_f32_e32 v133, v134, v133
	v_fmamk_f32 v134, v131, 0xbc800000, v62
	v_fmamk_f32 v136, v131, 0xbc800000, v60
	v_mul_f32_e32 v137, v137, v137
	v_mul_f32_e32 v135, v135, v135
	v_fmac_f32_e32 v137, v136, v136
	v_fmac_f32_e32 v135, v134, v134
	v_add_f32_e32 v134, v137, v135
	v_add_f32_e32 v133, v134, v133
	v_mov_b32_e32 v134, v133
	s_nop 1
	v_permlane16_swap_b32_e32 v134, v133
	s_nop 1
	s_waitcnt lgkmcnt(0)
	v_add_f32_e32 v133, v133, v134
	v_mov_b32_e32 v134, v133
	s_nop 1
	v_permlane32_swap_b32_e32 v134, v133
	s_nop 1
	s_and_saveexec_b64 s[48:49], s[12:13]
	s_cbranch_execz .LBB0_405
	v_mul_f32_e32 v136, 0x3c800000, v131
	s_waitcnt lgkmcnt(0)
	v_add_f32_e32 v137, v133, v134
	ds_write_b64 v208, v[136:137] offset:5120
.LBB0_405:
	s_or_b64 exec, exec, s[48:49]
	s_waitcnt lgkmcnt(0)
	v_mov_b32_e32 v134, v125
	v_mov_b32_e32 v135, v126
	v_mov_b32_e32 v136, v124
	v_mov_b32_e32 v137, v127
	v_pk_add_f32 v[134:135], v[134:135], v[136:137]
	v_mov_b32_e32 v136, v117
	v_mov_b32_e32 v137, v118
	v_mov_b32_e32 v138, v116
	v_mov_b32_e32 v139, v119
	v_pk_add_f32 v[136:137], v[136:137], v[138:139]
	v_add_f32_e32 v131, v134, v135
	v_pk_add_f32 v[136:137], v[136:137], v[136:137] op_sel_hi:[0,1]
	v_add_f32_e32 v135, 0, v131
	v_add_f32_e32 v139, v108, v109
	v_add_f32_e32 v141, v110, v111
	v_mov_b32_e32 v138, v100
	v_mov_b32_e32 v140, v101
	v_mov_b32_e32 v136, v102
	v_mov_b32_e32 v134, v103
	v_pk_add_f32 v[138:139], v[138:139], v[140:141]
	v_pk_add_f32 v[134:135], v[136:137], v[134:135]
	s_nop 0
	v_pk_add_f32 v[134:135], v[138:139], v[134:135]
	s_nop 0
	v_add_f32_e32 v131, v134, v135
	v_mov_b32_e32 v133, v131
	s_nop 1
	v_permlane16_swap_b32_e32 v133, v131
	s_nop 1
	s_waitcnt lgkmcnt(0)
	v_add_f32_e32 v131, v131, v133
	v_mov_b32_e32 v133, v131
	s_nop 1
	v_permlane32_swap_b32_e32 v133, v131
	s_nop 1
	s_waitcnt lgkmcnt(0)
	v_add_f32_e32 v131, v131, v133
	v_fmamk_f32 v134, v131, 0xbc800000, v127
	v_fmamk_f32 v136, v131, 0xbc800000, v125
	v_fmamk_f32 v133, v131, 0xbc800000, v126
	v_fmamk_f32 v135, v131, 0xbc800000, v124
	v_mul_f32_e32 v136, v136, v136
	v_mul_f32_e32 v134, v134, v134
	v_fmac_f32_e32 v136, v135, v135
	v_fmac_f32_e32 v134, v133, v133
	v_fmamk_f32 v135, v131, 0xbc800000, v119
	v_fmamk_f32 v137, v131, 0xbc800000, v117
	v_add_f32_e32 v133, v136, v134
	v_fmamk_f32 v134, v131, 0xbc800000, v118
	v_fmamk_f32 v136, v131, 0xbc800000, v116
	v_mul_f32_e32 v137, v137, v137
	v_mul_f32_e32 v135, v135, v135
	v_fmac_f32_e32 v137, v136, v136
	v_fmac_f32_e32 v135, v134, v134
	v_add_f32_e32 v134, v137, v135
	v_fmamk_f32 v135, v131, 0xbc800000, v111
	v_fmamk_f32 v137, v131, 0xbc800000, v109
	v_add_f32_e32 v133, v133, v134
	v_fmamk_f32 v134, v131, 0xbc800000, v110
	v_fmamk_f32 v136, v131, 0xbc800000, v108
	v_mul_f32_e32 v137, v137, v137
	v_mul_f32_e32 v135, v135, v135
	v_fmac_f32_e32 v137, v136, v136
	v_fmac_f32_e32 v135, v134, v134
	v_add_f32_e32 v134, v137, v135
	v_fmamk_f32 v135, v131, 0xbc800000, v103
	v_fmamk_f32 v137, v131, 0xbc800000, v101
	v_add_f32_e32 v133, v134, v133
	v_fmamk_f32 v134, v131, 0xbc800000, v102
	v_fmamk_f32 v136, v131, 0xbc800000, v100
	v_mul_f32_e32 v137, v137, v137
	v_mul_f32_e32 v135, v135, v135
	v_fmac_f32_e32 v137, v136, v136
	v_fmac_f32_e32 v135, v134, v134
	v_add_f32_e32 v134, v137, v135
	v_add_f32_e32 v133, v134, v133
	v_mov_b32_e32 v132, v133
	s_nop 1
	v_permlane16_swap_b32_e32 v132, v133
	s_nop 1
	s_waitcnt lgkmcnt(0)
	v_add_f32_e32 v132, v133, v132
	v_mov_b32_e32 v130, v132
	s_nop 1
	v_permlane32_swap_b32_e32 v130, v132
	s_nop 1
	s_and_saveexec_b64 s[48:49], s[12:13]
	s_cbranch_execz .LBB0_407
	v_mul_f32_e32 v134, 0x3c800000, v131
	s_waitcnt lgkmcnt(0)
	v_add_f32_e32 v135, v132, v130
	ds_write_b64 v208, v[134:135] offset:5632
